# EpiUp fast path: hand-written up-GEMM epilogue with hoisted loads (non-sample panels)
# speedup vs baseline: 1.0320x; 1.0320x over previous
;     __device__ __forceinline__ void operator()(const f32x4 (&acc)[2][2][4][2], const Unit& u, int wr, int wc, int fr, int fq) const {
;     ...
;         const bool samp = (u.pm == 64);
; #pragma unroll
;         for (int ai = 0; ai < 2; ++ai) {
;             const int rowb = u.pm * 256 + ai * 128 + wr * 64;
;             const int blk = 4 * u.pm + 2 * ai + wr;
;             float rs[4];
; #pragma unroll
;             for (int m = 0; m < 4; ++m) rs[m] = rsqrtf(SS[rowb + 16 * m + fr] * (1.0f / D) + EPS);
; #pragma unroll
;             for (int n = 0; n < 2; ++n) {
;                 f32x4 cg[4];
; #pragma unroll
;                 for (int bj = 0; bj < 2; ++bj) {
;                     const int oc = (bj ? FF : 0) + 128 * u.pn + 32 * wc + 8 * fq + 4 * n;
;                     const int cgc = 256 * u.pn + 128 * bj + 32 * wc + 8 * fq + 4 * n;
;                     const f32x4 cw0 = *(const f32x4*)(convw + oc), cw1 = *(const f32x4*)(convw + FF2 + oc), cw2 = *(const f32x4*)(convw + 2 * FF2 + oc), cb = *(const f32x4*)(convb + oc);
;                     f32x4 v[4];
; #pragma unroll
;                     for (int m = 0; m < 4; ++m) v[m] = acc[ai][bj][m][n] * rs[m];
;                     f32x4 hv = (f32x4){0.f, 0.f, 0.f, 0.f};
;                     if (!samp) {
;                         if ((blk & 31) != 0 && fr >= 14) hv = *(const f32x4*)(HALO + (size_t)(2 * blk + fr - 14) * FF2 + cgc);
.LBB0_892:
	s_cmp_lg_u32 s88, 64
	s_cbranch_scc1 .Lfe_begin
	s_cmp_eq_u32 s88, 64
	s_cselect_b64 s[84:85], -1, 0
	s_cmp_lg_u32 s88, 64
	s_cselect_b64 s[14:15], -1, 0
	s_lshl_b32 s77, s88, 8
	v_readlane_b32 s13, v236, 19
	s_add_i32 s77, s77, s13
	v_or_b32_e32 v202, s77, v153
	v_ashrrev_i32_e32 v203, 31, v202
	v_lshl_add_u64 v[128:129], v[202:203], 2, s[42:43]
	global_load_dword v128, v[128:129], off
	v_or_b32_e32 v200, 16, v202
	s_lshl_b32 s75, s88, 2
	s_lshl_b32 s86, s12, 7
	v_ashrrev_i32_e32 v201, 31, v200
	v_or_b32_e32 v198, 32, v202
	s_add_i32 s75, s75, s73
	v_or_b32_e32 v174, s86, v215
	v_ashrrev_i32_e32 v199, 31, v198
	v_or_b32_e32 v196, 48, v202
	v_lshl_or_b32 v170, s12, 8, v215
	v_ashrrev_i32_e32 v197, 31, v196
	s_and_b32 s12, s75, 31
	v_ashrrev_i32_e32 v175, 31, v174
	s_cmp_lg_u32 s12, 0
	v_lshlrev_b64 v[172:173], 2, v[174:175]
	s_cselect_b64 s[12:13], -1, 0
	v_lshl_add_u64 v[176:177], s[16:17], 0, v[172:173]
	v_lshl_add_u64 v[192:193], s[58:59], 0, v[172:173]
	v_lshl_add_u64 v[194:195], s[60:61], 0, v[172:173]
	v_lshl_add_u64 v[178:179], s[18:19], 0, v[172:173]
	s_and_b64 s[90:91], s[12:13], s[10:11]
	global_load_dwordx4 v[144:147], v[176:177], off
	global_load_dwordx4 v[132:135], v[192:193], off
	global_load_dwordx4 v[148:151], v[178:179], off
	s_waitcnt vmcnt(0)
	v_fmamk_f32 v128, v128, 0x3a800000, v218
	v_cmp_gt_f32_e32 vcc, s1, v128
	v_mul_f32_e32 v129, 0x4b800000, v128
	s_nop 0
	v_cndmask_b32_e32 v128, v128, v129, vcc
	v_rsq_f32_e32 v128, v128
	s_nop 0
	v_mul_f32_e32 v129, 0x45800000, v128
	v_cndmask_b32_e32 v206, v128, v129, vcc
	v_lshl_add_u64 v[128:129], v[200:201], 2, s[42:43]
	global_load_dword v182, v[128:129], off
	v_lshl_add_u64 v[128:129], v[198:199], 2, s[42:43]
	global_load_dword v181, v[128:129], off
	v_lshl_add_u64 v[128:129], v[196:197], 2, s[42:43]
	global_load_dword v180, v[128:129], off
	v_lshl_add_u32 v128, s75, 1, v216
	v_mad_i64_i32 v[208:209], s[12:13], v128, s4, 0
	global_load_dwordx4 v[128:131], v[194:195], off
	v_pk_mul_f32 v[126:127], v[126:127], v[206:207] op_sel_hi:[1,0]
	v_pk_mul_f32 v[124:125], v[124:125], v[206:207] op_sel_hi:[1,0]
	s_mov_b64 s[12:13], -1
	s_and_b64 vcc, exec, s[84:85]
	s_cbranch_vccnz .LBB0_896
	v_mov_b32_e32 v136, 0
	v_mov_b32_e32 v137, 0
	v_mov_b32_e32 v138, 0
	v_mov_b32_e32 v139, 0
	s_and_saveexec_b64 s[12:13], s[90:91]
	s_cbranch_execz .LBB0_895
	v_lshl_add_u64 v[136:137], s[44:45], 0, v[208:209]
	v_ashrrev_i32_e32 v171, 31, v170
	v_lshl_add_u64 v[136:137], v[170:171], 2, v[136:137]
	global_load_dwordx4 v[136:139], v[136:137], off

;     __device__ __forceinline__ void operator()(const f32x4 (&acc)[2][2][4][2], const Unit& u, int wr, int wc, int fr, int fq) const {
;     ...
;             const int rowb = u.pm * 256 + ai * 128 + wr * 64;
;             const int blk = 4 * u.pm + 2 * ai + wr;
;             float rs[4];
; #pragma unroll
;             for (int m = 0; m < 4; ++m) rs[m] = rsqrtf(SS[rowb + 16 * m + fr] * (1.0f / D) + EPS);
; #pragma unroll
;             for (int n = 0; n < 2; ++n) {
;                 f32x4 cg[4];
; #pragma unroll
;                 for (int bj = 0; bj < 2; ++bj) {
;                     const int oc = (bj ? FF : 0) + 128 * u.pn + 32 * wc + 8 * fq + 4 * n;
;                     const int cgc = 256 * u.pn + 128 * bj + 32 * wc + 8 * fq + 4 * n;
;                     const f32x4 cw0 = *(const f32x4*)(convw + oc), cw1 = *(const f32x4*)(convw + FF2 + oc), cw2 = *(const f32x4*)(convw + 2 * FF2 + oc), cb = *(const f32x4*)(convb + oc);
;                     f32x4 v[4];
; #pragma unroll
;                     for (int m = 0; m < 4; ++m) v[m] = acc[ai][bj][m][n] * rs[m];
;                     f32x4 hv = (f32x4){0.f, 0.f, 0.f, 0.f};
;                     if (!samp) {
;                         if ((blk & 31) != 0 && fr >= 14) hv = *(const f32x4*)(HALO + (size_t)(2 * blk + fr - 14) * FF2 + cgc);
.Lfe_begin:
	v_readlane_b32 s13, v236, 19
	s_lshl_b32 s77, s88, 8
	s_lshl_b32 s86, s12, 7
	s_lshl_b32 s75, s88, 2
	s_add_i32 s75, s75, s73
	s_add_i32 s77, s77, s13
	v_add_u32_e32 v246, s77, v153
	v_lshlrev_b32_e32 v247, 2, v246
	global_load_dword v238, v247, s[42:43]
	global_load_dword v239, v247, s[42:43] offset:64
	global_load_dword v240, v247, s[42:43] offset:128
	global_load_dword v241, v247, s[42:43] offset:192
	global_load_dword v242, v247, s[42:43] offset:512
	global_load_dword v243, v247, s[42:43] offset:576
	global_load_dword v244, v247, s[42:43] offset:640
	global_load_dword v245, v247, s[42:43] offset:704
	v_add_u32_e32 v248, s86, v215
	v_lshlrev_b32_e32 v237, 2, v248
	v_add_u32_e32 v250, 0x2c00, v237
	global_load_dwordx4 v[170:173], v237, s[16:17]
	global_load_dwordx4 v[174:177], v237, s[16:17] offset:16
	global_load_dwordx4 v[178:181], v250, s[16:17]
	global_load_dwordx4 v[182:185], v250, s[16:17] offset:16
	global_load_dwordx4 v[186:189], v237, s[58:59]
	global_load_dwordx4 v[190:193], v237, s[58:59] offset:16
	global_load_dwordx4 v[194:197], v250, s[58:59]
	global_load_dwordx4 v[198:201], v250, s[58:59] offset:16
	global_load_dwordx4 v[202:205], v237, s[60:61]
	global_load_dwordx4 v[206:209], v237, s[60:61] offset:16
	global_load_dwordx4 v[210:213], v250, s[60:61]
	global_load_dwordx4 v[128:131], v250, s[60:61] offset:16
	global_load_dwordx4 v[132:135], v237, s[18:19]
	global_load_dwordx4 v[136:139], v237, s[18:19] offset:16
	global_load_dwordx4 v[140:143], v250, s[18:19]
	global_load_dwordx4 v[144:147], v250, s[18:19] offset:16
	v_mul_u32_u24_e32 v151, 0x1600, v246
	v_lshl_add_u32 v151, v248, 1, v151
	v_mov_b32_e32 v220, 0
	v_mov_b32_e32 v221, 0
	v_mov_b32_e32 v222, 0
	v_mov_b32_e32 v223, 0
	v_mov_b32_e32 v224, 0
	v_mov_b32_e32 v225, 0
	v_mov_b32_e32 v226, 0
	v_mov_b32_e32 v227, 0
	v_mov_b32_e32 v228, 0
	v_mov_b32_e32 v229, 0
	v_mov_b32_e32 v230, 0
	v_mov_b32_e32 v231, 0
	v_mov_b32_e32 v232, 0
	v_mov_b32_e32 v233, 0
	v_mov_b32_e32 v234, 0
	v_mov_b32_e32 v235, 0
	s_mul_i32 s56, s75, 0xb000
	s_lshl_b32 s57, s12, 10
	s_add_i32 s56, s56, s57
	v_mul_i32_i24_e32 v150, 0x5800, v216
	v_lshl_add_u32 v150, v215, 2, v150
	v_add_u32_e32 v150, s56, v150
	s_and_b32 s14, s75, 31
	s_cbranch_scc0 .Lfe_nohalo0
	s_mov_b64 s[14:15], exec
	s_mov_b64 exec, s[10:11]
	global_load_dwordx4 v[220:223], v150, s[44:45]
	global_load_dwordx4 v[224:227], v150, s[44:45] offset:16
	global_load_dwordx4 v[228:231], v150, s[44:45] offset:512
	global_load_dwordx4 v[232:235], v150, s[44:45] offset:528
	s_mov_b64 exec, s[14:15]
.Lfe_nohalo0:
	s_waitcnt vmcnt(16)
	v_fmamk_f32 v238, v238, 0x3a800000, v218
	v_fmamk_f32 v239, v239, 0x3a800000, v218
	v_fmamk_f32 v240, v240, 0x3a800000, v218
	v_fmamk_f32 v241, v241, 0x3a800000, v218
	v_fmamk_f32 v242, v242, 0x3a800000, v218
	v_fmamk_f32 v243, v243, 0x3a800000, v218
	v_fmamk_f32 v244, v244, 0x3a800000, v218
	v_fmamk_f32 v245, v245, 0x3a800000, v218
	v_rsq_f32_e32 v238, v238
	v_rsq_f32_e32 v239, v239
	v_rsq_f32_e32 v240, v240
	v_rsq_f32_e32 v241, v241
	v_rsq_f32_e32 v242, v242
	v_rsq_f32_e32 v243, v243
	v_rsq_f32_e32 v244, v244
	v_rsq_f32_e32 v245, v245
	v_pk_mul_f32 v[124:125], v[124:125], v[238:239] op_sel_hi:[1,0]
	v_pk_mul_f32 v[126:127], v[126:127], v[238:239] op_sel_hi:[1,0]
	v_pk_mul_f32 v[92:93], v[92:93], v[238:239] op_sel_hi:[1,0]
	v_pk_mul_f32 v[94:95], v[94:95], v[238:239] op_sel_hi:[1,0]
	v_pk_mul_f32 v[108:109], v[108:109], v[238:239] op_sel_hi:[1,0]
	v_pk_mul_f32 v[110:111], v[110:111], v[238:239] op_sel_hi:[1,0]
	v_pk_mul_f32 v[76:77], v[76:77], v[238:239] op_sel_hi:[1,0]
	v_pk_mul_f32 v[78:79], v[78:79], v[238:239] op_sel_hi:[1,0]
	v_pk_mul_f32 v[120:121], v[120:121], v[238:239] op_sel:[0,1] op_sel_hi:[1,1]
	v_pk_mul_f32 v[122:123], v[122:123], v[238:239] op_sel:[0,1] op_sel_hi:[1,1]
	v_pk_mul_f32 v[88:89], v[88:89], v[238:239] op_sel:[0,1] op_sel_hi:[1,1]
	v_pk_mul_f32 v[90:91], v[90:91], v[238:239] op_sel:[0,1] op_sel_hi:[1,1]
	v_pk_mul_f32 v[104:105], v[104:105], v[238:239] op_sel:[0,1] op_sel_hi:[1,1]
	v_pk_mul_f32 v[106:107], v[106:107], v[238:239] op_sel:[0,1] op_sel_hi:[1,1]
	v_pk_mul_f32 v[72:73], v[72:73], v[238:239] op_sel:[0,1] op_sel_hi:[1,1]
	v_pk_mul_f32 v[74:75], v[74:75], v[238:239] op_sel:[0,1] op_sel_hi:[1,1]
	v_pk_mul_f32 v[116:117], v[116:117], v[240:241] op_sel_hi:[1,0]
	v_pk_mul_f32 v[118:119], v[118:119], v[240:241] op_sel_hi:[1,0]
	v_pk_mul_f32 v[84:85], v[84:85], v[240:241] op_sel_hi:[1,0]
	v_pk_mul_f32 v[86:87], v[86:87], v[240:241] op_sel_hi:[1,0]
	v_pk_mul_f32 v[100:101], v[100:101], v[240:241] op_sel_hi:[1,0]
	v_pk_mul_f32 v[102:103], v[102:103], v[240:241] op_sel_hi:[1,0]
	v_pk_mul_f32 v[68:69], v[68:69], v[240:241] op_sel_hi:[1,0]
	v_pk_mul_f32 v[70:71], v[70:71], v[240:241] op_sel_hi:[1,0]
	v_pk_mul_f32 v[112:113], v[112:113], v[240:241] op_sel:[0,1] op_sel_hi:[1,1]
	v_pk_mul_f32 v[114:115], v[114:115], v[240:241] op_sel:[0,1] op_sel_hi:[1,1]
	v_pk_mul_f32 v[80:81], v[80:81], v[240:241] op_sel:[0,1] op_sel_hi:[1,1]
	v_pk_mul_f32 v[82:83], v[82:83], v[240:241] op_sel:[0,1] op_sel_hi:[1,1]
	v_pk_mul_f32 v[96:97], v[96:97], v[240:241] op_sel:[0,1] op_sel_hi:[1,1]
	v_pk_mul_f32 v[98:99], v[98:99], v[240:241] op_sel:[0,1] op_sel_hi:[1,1]
	v_pk_mul_f32 v[64:65], v[64:65], v[240:241] op_sel:[0,1] op_sel_hi:[1,1]
	v_pk_mul_f32 v[66:67], v[66:67], v[240:241] op_sel:[0,1] op_sel_hi:[1,1]
	v_pk_mul_f32 v[60:61], v[60:61], v[242:243] op_sel_hi:[1,0]
	v_pk_mul_f32 v[62:63], v[62:63], v[242:243] op_sel_hi:[1,0]
	v_pk_mul_f32 v[28:29], v[28:29], v[242:243] op_sel_hi:[1,0]
	v_pk_mul_f32 v[30:31], v[30:31], v[242:243] op_sel_hi:[1,0]
	v_pk_mul_f32 v[44:45], v[44:45], v[242:243] op_sel_hi:[1,0]
; __device__ __forceinline__ f32x2 gelu_pk(f32x2 v) {
;     const f32x2 av = __builtin_elementwise_abs(v), d = av * 0.2316418882f + 1.0f;
;     __device__ __forceinline__ void operator()(const f32x4 (&acc)[2][2][4][2], const Unit& u, int wr, int wc, int fr, int fq) const {
;     ...
; #pragma unroll
;                     for (int m = 0; m < 4; ++m) {
;                         f32x4 cv;
;                         if (!samp) {
;                             const f32x4 prev = m ? v[m - 1] : hv;
; #pragma unroll
;                             for (int e = 0; e < 4; ++e) {
;                                 const int vi = __float_as_int(v[m][e]), pi = __float_as_int(prev[e]);
;                                 const int o1 = __builtin_amdgcn_mov_dpp(pi, 0x121, 0xf, 0xf, false);
;                                 const int o2 = __builtin_amdgcn_mov_dpp(pi, 0x122, 0xf, 0xf, false);
;                                 const float p1 = __int_as_float(__builtin_amdgcn_update_dpp(o1, vi, 0x111, 0xf, 0xf, false));
;                                 const float p2 = __int_as_float(__builtin_amdgcn_update_dpp(o2, vi, 0x112, 0xf, 0xf, false));
;                                 cv[e] = cb[e] + cw0[e] * p2 + cw1[e] * p1 + cw2[e] * v[m][e];
;                             }
;                         } else {
;                             const int ns = rowb + 16 * m + fr - MP;
;                             f32x4 s0 = (f32x4){0.f, 0.f, 0.f, 0.f}, s1 = s0;
;                             if (ns < NS) {
;                                 s0 = *(const f32x4*)(state + (size_t)(ns * 2 + 0) * FF2 + oc); s1 = *(const f32x4*)(state + (size_t)(ns * 2 + 1) * FF2 + oc);
;                                 *(f32x4*)(ncs + (size_t)(ns * 2 + 0) * FF2 + oc) = s1; *(f32x4*)(ncs + (size_t)(ns * 2 + 1) * FF2 + oc) = v[m];
;                             }
;                             cv = cb + cw0 * s0 + cw1 * s1 + cw2 * v[m];
;                         }
;                         if (bj == 0) cg[m] = gelu4(cv);
;                         else {
;                             const f32x4 r = cg[m] * cv;
;                             v2u w; w.x = cvt_pk_bf16(r[0], r[1]); w.y = cvt_pk_bf16(r[2], r[3]);
;                             *(v2u*)(ACT + (size_t)(rowb + 16 * m + fr) * FF + 128 * u.pn + 32 * wc + 8 * fq + 4 * n) = w;
;                         }
	v_pk_mul_f32 v[46:47], v[46:47], v[242:243] op_sel_hi:[1,0]
	v_pk_mul_f32 v[12:13], v[12:13], v[242:243] op_sel_hi:[1,0]
	v_pk_mul_f32 v[14:15], v[14:15], v[242:243] op_sel_hi:[1,0]
	v_pk_mul_f32 v[52:53], v[52:53], v[242:243] op_sel:[0,1] op_sel_hi:[1,1]
	v_pk_mul_f32 v[54:55], v[54:55], v[242:243] op_sel:[0,1] op_sel_hi:[1,1]
	v_pk_mul_f32 v[20:21], v[20:21], v[242:243] op_sel:[0,1] op_sel_hi:[1,1]
	v_pk_mul_f32 v[22:23], v[22:23], v[242:243] op_sel:[0,1] op_sel_hi:[1,1]
	v_pk_mul_f32 v[36:37], v[36:37], v[242:243] op_sel:[0,1] op_sel_hi:[1,1]
	v_pk_mul_f32 v[38:39], v[38:39], v[242:243] op_sel:[0,1] op_sel_hi:[1,1]
	v_pk_mul_f32 v[4:5], v[4:5], v[242:243] op_sel:[0,1] op_sel_hi:[1,1]
	v_pk_mul_f32 v[6:7], v[6:7], v[242:243] op_sel:[0,1] op_sel_hi:[1,1]
	v_pk_mul_f32 v[48:49], v[48:49], v[244:245] op_sel_hi:[1,0]
	v_pk_mul_f32 v[50:51], v[50:51], v[244:245] op_sel_hi:[1,0]
	v_pk_mul_f32 v[16:17], v[16:17], v[244:245] op_sel_hi:[1,0]
	v_pk_mul_f32 v[18:19], v[18:19], v[244:245] op_sel_hi:[1,0]
	v_pk_mul_f32 v[32:33], v[32:33], v[244:245] op_sel_hi:[1,0]
	v_pk_mul_f32 v[34:35], v[34:35], v[244:245] op_sel_hi:[1,0]
	v_pk_mul_f32 v[0:1], v[0:1], v[244:245] op_sel_hi:[1,0]
	v_pk_mul_f32 v[2:3], v[2:3], v[244:245] op_sel_hi:[1,0]
	v_pk_mul_f32 v[56:57], v[56:57], v[244:245] op_sel:[0,1] op_sel_hi:[1,1]
	v_pk_mul_f32 v[58:59], v[58:59], v[244:245] op_sel:[0,1] op_sel_hi:[1,1]
	v_pk_mul_f32 v[24:25], v[24:25], v[244:245] op_sel:[0,1] op_sel_hi:[1,1]
	v_pk_mul_f32 v[26:27], v[26:27], v[244:245] op_sel:[0,1] op_sel_hi:[1,1]
	v_pk_mul_f32 v[40:41], v[40:41], v[244:245] op_sel:[0,1] op_sel_hi:[1,1]
	v_pk_mul_f32 v[42:43], v[42:43], v[244:245] op_sel:[0,1] op_sel_hi:[1,1]
	v_pk_mul_f32 v[8:9], v[8:9], v[244:245] op_sel:[0,1] op_sel_hi:[1,1]
	v_pk_mul_f32 v[10:11], v[10:11], v[244:245] op_sel:[0,1] op_sel_hi:[1,1]
	s_waitcnt vmcnt(0)
	v_mov_b32_dpp v246, v220 row_ror:1 row_mask:0xf bank_mask:0xf
	v_mov_b32_dpp v250, v220 row_ror:2 row_mask:0xf bank_mask:0xf
	v_mov_b32_dpp v247, v221 row_ror:1 row_mask:0xf bank_mask:0xf
	v_mov_b32_dpp v251, v221 row_ror:2 row_mask:0xf bank_mask:0xf
	v_mov_b32_dpp v248, v222 row_ror:1 row_mask:0xf bank_mask:0xf
	v_mov_b32_dpp v252, v222 row_ror:2 row_mask:0xf bank_mask:0xf
	v_mov_b32_dpp v249, v223 row_ror:1 row_mask:0xf bank_mask:0xf
	v_mov_b32_dpp v253, v223 row_ror:2 row_mask:0xf bank_mask:0xf
	v_mov_b32_dpp v246, v124 row_shr:1 row_mask:0xf bank_mask:0xf
	v_mov_b32_dpp v250, v124 row_shr:2 row_mask:0xf bank_mask:0xf
	v_mov_b32_dpp v247, v125 row_shr:1 row_mask:0xf bank_mask:0xf
	v_mov_b32_dpp v251, v125 row_shr:2 row_mask:0xf bank_mask:0xf
	v_mov_b32_dpp v248, v126 row_shr:1 row_mask:0xf bank_mask:0xf
	v_mov_b32_dpp v252, v126 row_shr:2 row_mask:0xf bank_mask:0xf
	v_mov_b32_dpp v249, v127 row_shr:1 row_mask:0xf bank_mask:0xf
	v_mov_b32_dpp v253, v127 row_shr:2 row_mask:0xf bank_mask:0xf
	v_pk_fma_f32 v[254:255], v[170:171], v[250:251], v[132:133]
	v_pk_fma_f32 v[148:149], v[172:173], v[252:253], v[134:135]
	v_pk_fma_f32 v[254:255], v[186:187], v[246:247], v[254:255]
	v_pk_fma_f32 v[148:149], v[188:189], v[248:249], v[148:149]
	v_pk_fma_f32 v[254:255], v[202:203], v[124:125], v[254:255]
	v_pk_fma_f32 v[148:149], v[204:205], v[126:127], v[148:149]
	v_and_b32_e32 v246, 0x7fffffff, v254
	v_and_b32_e32 v247, 0x7fffffff, v255
	v_and_b32_e32 v250, 0x7fffffff, v148
	v_and_b32_e32 v251, 0x7fffffff, v149
	v_pk_fma_f32 v[246:247], v[246:247], s[38:39], 1.0 op_sel_hi:[1,0,0]
	v_pk_fma_f32 v[250:251], v[250:251], s[38:39], 1.0 op_sel_hi:[1,0,0]
	v_pk_mul_f32 v[248:249], v[254:255], v[254:255]
	v_pk_mul_f32 v[252:253], v[148:149], v[148:149]
	v_rcp_f32_e32 v246, v246
	v_rcp_f32_e32 v247, v247
	v_rcp_f32_e32 v250, v250
	v_rcp_f32_e32 v251, v251
	v_pk_mul_f32 v[248:249], v[248:249], s[72:73] op_sel_hi:[1,0]
	v_pk_mul_f32 v[252:253], v[252:253], s[72:73] op_sel_hi:[1,0]
	v_mov_b64_e32 v[238:239], s[64:65]
	v_mov_b64_e32 v[240:241], s[64:65]
	v_exp_f32_e32 v248, v248
	v_exp_f32_e32 v249, v249
	v_exp_f32_e32 v252, v252
	v_exp_f32_e32 v253, v253
	v_pk_fma_f32 v[238:239], v[246:247], s[62:63], v[238:239] op_sel_hi:[1,0,0]
	v_pk_fma_f32 v[240:241], v[250:251], s[62:63], v[240:241] op_sel_hi:[1,0,0]
	v_pk_fma_f32 v[238:239], v[246:247], v[238:239], s[66:67] op_sel_hi:[1,1,0]
	v_pk_fma_f32 v[240:241], v[250:251], v[240:241], s[66:67] op_sel_hi:[1,1,0]
	v_pk_fma_f32 v[238:239], v[246:247], v[238:239], s[68:69] op_sel_hi:[1,1,0]
	v_pk_fma_f32 v[240:241], v[250:251], v[240:241], s[68:69] op_sel_hi:[1,1,0]
	v_pk_fma_f32 v[238:239], v[246:247], v[238:239], s[70:71] op_sel_hi:[1,1,0]
	v_pk_fma_f32 v[240:241], v[250:251], v[240:241], s[70:71] op_sel_hi:[1,1,0]
	v_pk_mul_f32 v[238:239], v[246:247], v[238:239]
	v_pk_mul_f32 v[240:241], v[250:251], v[240:241]
	v_pk_mul_f32 v[238:239], v[248:249], v[238:239]
	v_pk_mul_f32 v[240:241], v[252:253], v[240:241]
	v_cmp_gt_f32_e64 vcc, 0, v254
	v_cmp_gt_f32_e64 s[56:57], 0, v148
	v_cmp_gt_f32_e64 s[14:15], 0, v255
	v_cmp_gt_f32_e64 s[92:93], 0, v149
	v_pk_mul_f32 v[248:249], v[254:255], v[238:239]
	v_pk_mul_f32 v[252:253], v[148:149], v[240:241]
	v_pk_fma_f32 v[238:239], v[254:255], v[238:239], v[254:255] neg_lo:[1,0,0] neg_hi:[1,0,0]
	v_pk_fma_f32 v[240:241], v[148:149], v[240:241], v[148:149] neg_lo:[1,0,0] neg_hi:[1,0,0]
	v_cndmask_b32_e64 v238, v238, v248, vcc
	v_cndmask_b32_e64 v240, v240, v252, s[56:57]
	v_cndmask_b32_e64 v239, v239, v249, s[14:15]
	v_cndmask_b32_e64 v241, v241, v253, s[92:93]
	v_mov_b32_dpp v246, v228 row_ror:1 row_mask:0xf bank_mask:0xf
	v_mov_b32_dpp v250, v228 row_ror:2 row_mask:0xf bank_mask:0xf
	v_mov_b32_dpp v247, v229 row_ror:1 row_mask:0xf bank_mask:0xf
; __device__ __forceinline__ f32x2 gelu_pk(f32x2 v) {
;     const f32x2 av = __builtin_elementwise_abs(v), d = av * 0.2316418882f + 1.0f;
;     __device__ __forceinline__ void operator()(const f32x4 (&acc)[2][2][4][2], const Unit& u, int wr, int wc, int fr, int fq) const {
;     ...
; #pragma unroll
;                     for (int m = 0; m < 4; ++m) {
;                         f32x4 cv;
;                         if (!samp) {
;                             const f32x4 prev = m ? v[m - 1] : hv;
; #pragma unroll
;                             for (int e = 0; e < 4; ++e) {
;                                 const int vi = __float_as_int(v[m][e]), pi = __float_as_int(prev[e]);
;                                 const int o1 = __builtin_amdgcn_mov_dpp(pi, 0x121, 0xf, 0xf, false);
;                                 const int o2 = __builtin_amdgcn_mov_dpp(pi, 0x122, 0xf, 0xf, false);
;                                 const float p1 = __int_as_float(__builtin_amdgcn_update_dpp(o1, vi, 0x111, 0xf, 0xf, false));
;                                 const float p2 = __int_as_float(__builtin_amdgcn_update_dpp(o2, vi, 0x112, 0xf, 0xf, false));
;                                 cv[e] = cb[e] + cw0[e] * p2 + cw1[e] * p1 + cw2[e] * v[m][e];
;                             }
;                         } else {
;                             const int ns = rowb + 16 * m + fr - MP;
;                             f32x4 s0 = (f32x4){0.f, 0.f, 0.f, 0.f}, s1 = s0;
;                             if (ns < NS) {
;                                 s0 = *(const f32x4*)(state + (size_t)(ns * 2 + 0) * FF2 + oc); s1 = *(const f32x4*)(state + (size_t)(ns * 2 + 1) * FF2 + oc);
;                                 *(f32x4*)(ncs + (size_t)(ns * 2 + 0) * FF2 + oc) = s1; *(f32x4*)(ncs + (size_t)(ns * 2 + 1) * FF2 + oc) = v[m];
;                             }
;                             cv = cb + cw0 * s0 + cw1 * s1 + cw2 * v[m];
;                         }
;                         if (bj == 0) cg[m] = gelu4(cv);
;                         else {
;                             const f32x4 r = cg[m] * cv;
;                             v2u w; w.x = cvt_pk_bf16(r[0], r[1]); w.y = cvt_pk_bf16(r[2], r[3]);
;                             *(v2u*)(ACT + (size_t)(rowb + 16 * m + fr) * FF + 128 * u.pn + 32 * wc + 8 * fq + 4 * n) = w;
;                         }
	v_mov_b32_dpp v251, v229 row_ror:2 row_mask:0xf bank_mask:0xf
	v_mov_b32_dpp v248, v230 row_ror:1 row_mask:0xf bank_mask:0xf
	v_mov_b32_dpp v252, v230 row_ror:2 row_mask:0xf bank_mask:0xf
	v_mov_b32_dpp v249, v231 row_ror:1 row_mask:0xf bank_mask:0xf
	v_mov_b32_dpp v253, v231 row_ror:2 row_mask:0xf bank_mask:0xf
	v_mov_b32_dpp v246, v108 row_shr:1 row_mask:0xf bank_mask:0xf
	v_mov_b32_dpp v250, v108 row_shr:2 row_mask:0xf bank_mask:0xf
	v_mov_b32_dpp v247, v109 row_shr:1 row_mask:0xf bank_mask:0xf
	v_mov_b32_dpp v251, v109 row_shr:2 row_mask:0xf bank_mask:0xf
	v_mov_b32_dpp v248, v110 row_shr:1 row_mask:0xf bank_mask:0xf
	v_mov_b32_dpp v252, v110 row_shr:2 row_mask:0xf bank_mask:0xf
	v_mov_b32_dpp v249, v111 row_shr:1 row_mask:0xf bank_mask:0xf
	v_mov_b32_dpp v253, v111 row_shr:2 row_mask:0xf bank_mask:0xf
	v_pk_fma_f32 v[254:255], v[178:179], v[250:251], v[140:141]
	v_pk_fma_f32 v[148:149], v[180:181], v[252:253], v[142:143]
	v_pk_fma_f32 v[254:255], v[194:195], v[246:247], v[254:255]
	v_pk_fma_f32 v[148:149], v[196:197], v[248:249], v[148:149]
	v_pk_fma_f32 v[254:255], v[210:211], v[108:109], v[254:255]
	v_pk_fma_f32 v[148:149], v[212:213], v[110:111], v[148:149]
	v_pk_mul_f32 v[254:255], v[238:239], v[254:255]
	v_pk_mul_f32 v[148:149], v[240:241], v[148:149]
	v_cvt_pk_bf16_f32 v242, v254, v255
	v_cvt_pk_bf16_f32 v243, v148, v149
	v_mov_b32_dpp v246, v224 row_ror:1 row_mask:0xf bank_mask:0xf
	v_mov_b32_dpp v250, v224 row_ror:2 row_mask:0xf bank_mask:0xf
	v_mov_b32_dpp v247, v225 row_ror:1 row_mask:0xf bank_mask:0xf
	v_mov_b32_dpp v251, v225 row_ror:2 row_mask:0xf bank_mask:0xf
	v_mov_b32_dpp v248, v226 row_ror:1 row_mask:0xf bank_mask:0xf
	v_mov_b32_dpp v252, v226 row_ror:2 row_mask:0xf bank_mask:0xf
	v_mov_b32_dpp v249, v227 row_ror:1 row_mask:0xf bank_mask:0xf
	v_mov_b32_dpp v253, v227 row_ror:2 row_mask:0xf bank_mask:0xf
	v_mov_b32_dpp v246, v92 row_shr:1 row_mask:0xf bank_mask:0xf
	v_mov_b32_dpp v250, v92 row_shr:2 row_mask:0xf bank_mask:0xf
	v_mov_b32_dpp v247, v93 row_shr:1 row_mask:0xf bank_mask:0xf
	v_mov_b32_dpp v251, v93 row_shr:2 row_mask:0xf bank_mask:0xf
	v_mov_b32_dpp v248, v94 row_shr:1 row_mask:0xf bank_mask:0xf
	v_mov_b32_dpp v252, v94 row_shr:2 row_mask:0xf bank_mask:0xf
	v_mov_b32_dpp v249, v95 row_shr:1 row_mask:0xf bank_mask:0xf
	v_mov_b32_dpp v253, v95 row_shr:2 row_mask:0xf bank_mask:0xf
	v_pk_fma_f32 v[254:255], v[174:175], v[250:251], v[136:137]
	v_pk_fma_f32 v[148:149], v[176:177], v[252:253], v[138:139]
	v_pk_fma_f32 v[254:255], v[190:191], v[246:247], v[254:255]
	v_pk_fma_f32 v[148:149], v[192:193], v[248:249], v[148:149]
	v_pk_fma_f32 v[254:255], v[206:207], v[92:93], v[254:255]
	v_pk_fma_f32 v[148:149], v[208:209], v[94:95], v[148:149]
	v_and_b32_e32 v246, 0x7fffffff, v254
	v_and_b32_e32 v247, 0x7fffffff, v255
	v_and_b32_e32 v250, 0x7fffffff, v148
	v_and_b32_e32 v251, 0x7fffffff, v149
	v_pk_fma_f32 v[246:247], v[246:247], s[38:39], 1.0 op_sel_hi:[1,0,0]
	v_pk_fma_f32 v[250:251], v[250:251], s[38:39], 1.0 op_sel_hi:[1,0,0]
	v_pk_mul_f32 v[248:249], v[254:255], v[254:255]
	v_pk_mul_f32 v[252:253], v[148:149], v[148:149]
	v_rcp_f32_e32 v246, v246
	v_rcp_f32_e32 v247, v247
	v_rcp_f32_e32 v250, v250
	v_rcp_f32_e32 v251, v251
	v_pk_mul_f32 v[248:249], v[248:249], s[72:73] op_sel_hi:[1,0]
	v_pk_mul_f32 v[252:253], v[252:253], s[72:73] op_sel_hi:[1,0]
	v_mov_b64_e32 v[238:239], s[64:65]
	v_mov_b64_e32 v[240:241], s[64:65]
	v_exp_f32_e32 v248, v248
	v_exp_f32_e32 v249, v249
	v_exp_f32_e32 v252, v252
	v_exp_f32_e32 v253, v253
	v_pk_fma_f32 v[238:239], v[246:247], s[62:63], v[238:239] op_sel_hi:[1,0,0]
	v_pk_fma_f32 v[240:241], v[250:251], s[62:63], v[240:241] op_sel_hi:[1,0,0]
	v_pk_fma_f32 v[238:239], v[246:247], v[238:239], s[66:67] op_sel_hi:[1,1,0]
	v_pk_fma_f32 v[240:241], v[250:251], v[240:241], s[66:67] op_sel_hi:[1,1,0]
	v_pk_fma_f32 v[238:239], v[246:247], v[238:239], s[68:69] op_sel_hi:[1,1,0]
	v_pk_fma_f32 v[240:241], v[250:251], v[240:241], s[68:69] op_sel_hi:[1,1,0]
	v_pk_fma_f32 v[238:239], v[246:247], v[238:239], s[70:71] op_sel_hi:[1,1,0]
	v_pk_fma_f32 v[240:241], v[250:251], v[240:241], s[70:71] op_sel_hi:[1,1,0]
	v_pk_mul_f32 v[238:239], v[246:247], v[238:239]
	v_pk_mul_f32 v[240:241], v[250:251], v[240:241]
	v_pk_mul_f32 v[238:239], v[248:249], v[238:239]
	v_pk_mul_f32 v[240:241], v[252:253], v[240:241]
	v_cmp_gt_f32_e64 vcc, 0, v254
	v_cmp_gt_f32_e64 s[56:57], 0, v148
	v_cmp_gt_f32_e64 s[14:15], 0, v255
	v_cmp_gt_f32_e64 s[92:93], 0, v149
	v_pk_mul_f32 v[248:249], v[254:255], v[238:239]
	v_pk_mul_f32 v[252:253], v[148:149], v[240:241]
	v_pk_fma_f32 v[238:239], v[254:255], v[238:239], v[254:255] neg_lo:[1,0,0] neg_hi:[1,0,0]
	v_pk_fma_f32 v[240:241], v[148:149], v[240:241], v[148:149] neg_lo:[1,0,0] neg_hi:[1,0,0]
	v_cndmask_b32_e64 v238, v238, v248, vcc
	v_cndmask_b32_e64 v240, v240, v252, s[56:57]
	v_cndmask_b32_e64 v239, v239, v249, s[14:15]
	v_cndmask_b32_e64 v241, v241, v253, s[92:93]
	v_mov_b32_dpp v246, v232 row_ror:1 row_mask:0xf bank_mask:0xf
	v_mov_b32_dpp v250, v232 row_ror:2 row_mask:0xf bank_mask:0xf
	v_mov_b32_dpp v247, v233 row_ror:1 row_mask:0xf bank_mask:0xf
	v_mov_b32_dpp v251, v233 row_ror:2 row_mask:0xf bank_mask:0xf
	v_mov_b32_dpp v248, v234 row_ror:1 row_mask:0xf bank_mask:0xf
	v_mov_b32_dpp v252, v234 row_ror:2 row_mask:0xf bank_mask:0xf
	v_mov_b32_dpp v249, v235 row_ror:1 row_mask:0xf bank_mask:0xf
	v_mov_b32_dpp v253, v235 row_ror:2 row_mask:0xf bank_mask:0xf
	v_mov_b32_dpp v246, v76 row_shr:1 row_mask:0xf bank_mask:0xf
	v_mov_b32_dpp v250, v76 row_shr:2 row_mask:0xf bank_mask:0xf
	v_mov_b32_dpp v247, v77 row_shr:1 row_mask:0xf bank_mask:0xf
;     __device__ __forceinline__ void operator()(const f32x4 (&acc)[2][2][4][2], const Unit& u, int wr, int wc, int fr, int fq) const {
;     ...
;                         if ((blk & 31) != 0 && fr >= 14) hv = *(const f32x4*)(HALO + (size_t)(2 * blk + fr - 14) * FF2 + cgc);
;                         if ((u.pm & 7) == 7 && ai == 1 && wr == 1 && fr >= 14) *(f32x4*)(ncp + (size_t)((u.pm >> 3) * 2 + (fr - 14)) * FF2 + oc) = v[3];
;                     }
; #pragma unroll
;                     for (int m = 0; m < 4; ++m) {
;                         f32x4 cv;
;                         if (!samp) {
;                             const f32x4 prev = m ? v[m - 1] : hv;
; #pragma unroll
;                             for (int e = 0; e < 4; ++e) {
;                                 const int vi = __float_as_int(v[m][e]), pi = __float_as_int(prev[e]);
;                                 const int o1 = __builtin_amdgcn_mov_dpp(pi, 0x121, 0xf, 0xf, false);
;                                 const int o2 = __builtin_amdgcn_mov_dpp(pi, 0x122, 0xf, 0xf, false);
;                                 const float p1 = __int_as_float(__builtin_amdgcn_update_dpp(o1, vi, 0x111, 0xf, 0xf, false));
;                                 const float p2 = __int_as_float(__builtin_amdgcn_update_dpp(o2, vi, 0x112, 0xf, 0xf, false));
;                                 cv[e] = cb[e] + cw0[e] * p2 + cw1[e] * p1 + cw2[e] * v[m][e];
;                             }
;                         } else {
;                             const int ns = rowb + 16 * m + fr - MP;
;                             f32x4 s0 = (f32x4){0.f, 0.f, 0.f, 0.f}, s1 = s0;
;                             if (ns < NS) {
;                                 s0 = *(const f32x4*)(state + (size_t)(ns * 2 + 0) * FF2 + oc); s1 = *(const f32x4*)(state + (size_t)(ns * 2 + 1) * FF2 + oc);
;                                 *(f32x4*)(ncs + (size_t)(ns * 2 + 0) * FF2 + oc) = s1; *(f32x4*)(ncs + (size_t)(ns * 2 + 1) * FF2 + oc) = v[m];
;                             }
;                             cv = cb + cw0 * s0 + cw1 * s1 + cw2 * v[m];
;                         }
;                         if (bj == 0) cg[m] = gelu4(cv);
;                         else {
;                             const f32x4 r = cg[m] * cv;
;                             v2u w; w.x = cvt_pk_bf16(r[0], r[1]); w.y = cvt_pk_bf16(r[2], r[3]);
	v_mov_b32_dpp v251, v77 row_shr:2 row_mask:0xf bank_mask:0xf
	v_mov_b32_dpp v248, v78 row_shr:1 row_mask:0xf bank_mask:0xf
	v_mov_b32_dpp v252, v78 row_shr:2 row_mask:0xf bank_mask:0xf
	v_mov_b32_dpp v249, v79 row_shr:1 row_mask:0xf bank_mask:0xf
	v_mov_b32_dpp v253, v79 row_shr:2 row_mask:0xf bank_mask:0xf
	v_pk_fma_f32 v[254:255], v[182:183], v[250:251], v[144:145]
	v_pk_fma_f32 v[148:149], v[184:185], v[252:253], v[146:147]
	v_pk_fma_f32 v[254:255], v[198:199], v[246:247], v[254:255]
	v_pk_fma_f32 v[148:149], v[200:201], v[248:249], v[148:149]
	v_pk_fma_f32 v[254:255], v[128:129], v[76:77], v[254:255]
	v_pk_fma_f32 v[148:149], v[130:131], v[78:79], v[148:149]
	v_pk_mul_f32 v[254:255], v[238:239], v[254:255]
	v_pk_mul_f32 v[148:149], v[240:241], v[148:149]
	v_cvt_pk_bf16_f32 v244, v254, v255
	v_cvt_pk_bf16_f32 v245, v148, v149
	global_store_dwordx4 v151, v[242:245], s[46:47]
	v_add_u32_e32 v150, 0x16000, v150
	s_mov_b64 s[14:15], exec
	s_mov_b64 exec, s[10:11]
	global_load_dwordx4 v[220:223], v150, s[44:45]
	global_load_dwordx4 v[224:227], v150, s[44:45] offset:16
	global_load_dwordx4 v[228:231], v150, s[44:45] offset:512
	global_load_dwordx4 v[232:235], v150, s[44:45] offset:528
	s_mov_b64 exec, s[14:15]
	v_mov_b32_dpp v246, v124 row_ror:1 row_mask:0xf bank_mask:0xf
	v_mov_b32_dpp v250, v124 row_ror:2 row_mask:0xf bank_mask:0xf
	v_mov_b32_dpp v247, v125 row_ror:1 row_mask:0xf bank_mask:0xf
	v_mov_b32_dpp v251, v125 row_ror:2 row_mask:0xf bank_mask:0xf
	v_mov_b32_dpp v248, v126 row_ror:1 row_mask:0xf bank_mask:0xf
	v_mov_b32_dpp v252, v126 row_ror:2 row_mask:0xf bank_mask:0xf
	v_mov_b32_dpp v249, v127 row_ror:1 row_mask:0xf bank_mask:0xf
	v_mov_b32_dpp v253, v127 row_ror:2 row_mask:0xf bank_mask:0xf
	v_mov_b32_dpp v246, v120 row_shr:1 row_mask:0xf bank_mask:0xf
	v_mov_b32_dpp v250, v120 row_shr:2 row_mask:0xf bank_mask:0xf
	v_mov_b32_dpp v247, v121 row_shr:1 row_mask:0xf bank_mask:0xf
	v_mov_b32_dpp v251, v121 row_shr:2 row_mask:0xf bank_mask:0xf
	v_mov_b32_dpp v248, v122 row_shr:1 row_mask:0xf bank_mask:0xf
	v_mov_b32_dpp v252, v122 row_shr:2 row_mask:0xf bank_mask:0xf
	v_mov_b32_dpp v249, v123 row_shr:1 row_mask:0xf bank_mask:0xf
	v_mov_b32_dpp v253, v123 row_shr:2 row_mask:0xf bank_mask:0xf
	v_pk_fma_f32 v[254:255], v[170:171], v[250:251], v[132:133]
	v_pk_fma_f32 v[148:149], v[172:173], v[252:253], v[134:135]
	v_pk_fma_f32 v[254:255], v[186:187], v[246:247], v[254:255]
	v_pk_fma_f32 v[148:149], v[188:189], v[248:249], v[148:149]
	v_pk_fma_f32 v[254:255], v[202:203], v[120:121], v[254:255]
	v_pk_fma_f32 v[148:149], v[204:205], v[122:123], v[148:149]
	v_and_b32_e32 v246, 0x7fffffff, v254
	v_and_b32_e32 v247, 0x7fffffff, v255
	v_and_b32_e32 v250, 0x7fffffff, v148
	v_and_b32_e32 v251, 0x7fffffff, v149
	v_pk_fma_f32 v[246:247], v[246:247], s[38:39], 1.0 op_sel_hi:[1,0,0]
	v_pk_fma_f32 v[250:251], v[250:251], s[38:39], 1.0 op_sel_hi:[1,0,0]
	v_pk_mul_f32 v[248:249], v[254:255], v[254:255]
	v_pk_mul_f32 v[252:253], v[148:149], v[148:149]
	v_rcp_f32_e32 v246, v246
	v_rcp_f32_e32 v247, v247
	v_rcp_f32_e32 v250, v250
	v_rcp_f32_e32 v251, v251
	v_pk_mul_f32 v[248:249], v[248:249], s[72:73] op_sel_hi:[1,0]
	v_pk_mul_f32 v[252:253], v[252:253], s[72:73] op_sel_hi:[1,0]
	v_mov_b64_e32 v[238:239], s[64:65]
	v_mov_b64_e32 v[240:241], s[64:65]
	v_exp_f32_e32 v248, v248
	v_exp_f32_e32 v249, v249
	v_exp_f32_e32 v252, v252
	v_exp_f32_e32 v253, v253
	v_pk_fma_f32 v[238:239], v[246:247], s[62:63], v[238:239] op_sel_hi:[1,0,0]
	v_pk_fma_f32 v[240:241], v[250:251], s[62:63], v[240:241] op_sel_hi:[1,0,0]
	v_pk_fma_f32 v[238:239], v[246:247], v[238:239], s[66:67] op_sel_hi:[1,1,0]
	v_pk_fma_f32 v[240:241], v[250:251], v[240:241], s[66:67] op_sel_hi:[1,1,0]
	v_pk_fma_f32 v[238:239], v[246:247], v[238:239], s[68:69] op_sel_hi:[1,1,0]
	v_pk_fma_f32 v[240:241], v[250:251], v[240:241], s[68:69] op_sel_hi:[1,1,0]
	v_pk_fma_f32 v[238:239], v[246:247], v[238:239], s[70:71] op_sel_hi:[1,1,0]
	v_pk_fma_f32 v[240:241], v[250:251], v[240:241], s[70:71] op_sel_hi:[1,1,0]
	v_pk_mul_f32 v[238:239], v[246:247], v[238:239]
	v_pk_mul_f32 v[240:241], v[250:251], v[240:241]
	v_pk_mul_f32 v[238:239], v[248:249], v[238:239]
	v_pk_mul_f32 v[240:241], v[252:253], v[240:241]
	v_cmp_gt_f32_e64 vcc, 0, v254
	v_cmp_gt_f32_e64 s[56:57], 0, v148
	v_cmp_gt_f32_e64 s[14:15], 0, v255
	v_cmp_gt_f32_e64 s[92:93], 0, v149
	v_pk_mul_f32 v[248:249], v[254:255], v[238:239]
	v_pk_mul_f32 v[252:253], v[148:149], v[240:241]
	v_pk_fma_f32 v[238:239], v[254:255], v[238:239], v[254:255] neg_lo:[1,0,0] neg_hi:[1,0,0]
	v_pk_fma_f32 v[240:241], v[148:149], v[240:241], v[148:149] neg_lo:[1,0,0] neg_hi:[1,0,0]
	v_cndmask_b32_e64 v238, v238, v248, vcc
	v_cndmask_b32_e64 v240, v240, v252, s[56:57]
	v_cndmask_b32_e64 v239, v239, v249, s[14:15]
	v_cndmask_b32_e64 v241, v241, v253, s[92:93]
	v_mov_b32_dpp v246, v108 row_ror:1 row_mask:0xf bank_mask:0xf
	v_mov_b32_dpp v250, v108 row_ror:2 row_mask:0xf bank_mask:0xf
	v_mov_b32_dpp v247, v109 row_ror:1 row_mask:0xf bank_mask:0xf
	v_mov_b32_dpp v251, v109 row_ror:2 row_mask:0xf bank_mask:0xf
	v_mov_b32_dpp v248, v110 row_ror:1 row_mask:0xf bank_mask:0xf
	v_mov_b32_dpp v252, v110 row_ror:2 row_mask:0xf bank_mask:0xf
	v_mov_b32_dpp v249, v111 row_ror:1 row_mask:0xf bank_mask:0xf
	v_mov_b32_dpp v253, v111 row_ror:2 row_mask:0xf bank_mask:0xf
	v_mov_b32_dpp v246, v104 row_shr:1 row_mask:0xf bank_mask:0xf
	v_mov_b32_dpp v250, v104 row_shr:2 row_mask:0xf bank_mask:0xf
	v_mov_b32_dpp v247, v105 row_shr:1 row_mask:0xf bank_mask:0xf
	v_mov_b32_dpp v251, v105 row_shr:2 row_mask:0xf bank_mask:0xf
	v_mov_b32_dpp v248, v106 row_shr:1 row_mask:0xf bank_mask:0xf
; __device__ __forceinline__ f32x2 gelu_pk(f32x2 v) {
;     const f32x2 av = __builtin_elementwise_abs(v), d = av * 0.2316418882f + 1.0f;
;     __device__ __forceinline__ void operator()(const f32x4 (&acc)[2][2][4][2], const Unit& u, int wr, int wc, int fr, int fq) const {
;     ...
; #pragma unroll
;                     for (int m = 0; m < 4; ++m) {
;                         f32x4 cv;
;                         if (!samp) {
;                             const f32x4 prev = m ? v[m - 1] : hv;
; #pragma unroll
;                             for (int e = 0; e < 4; ++e) {
;                                 const int vi = __float_as_int(v[m][e]), pi = __float_as_int(prev[e]);
;                                 const int o1 = __builtin_amdgcn_mov_dpp(pi, 0x121, 0xf, 0xf, false);
;                                 const int o2 = __builtin_amdgcn_mov_dpp(pi, 0x122, 0xf, 0xf, false);
;                                 const float p1 = __int_as_float(__builtin_amdgcn_update_dpp(o1, vi, 0x111, 0xf, 0xf, false));
;                                 const float p2 = __int_as_float(__builtin_amdgcn_update_dpp(o2, vi, 0x112, 0xf, 0xf, false));
;                                 cv[e] = cb[e] + cw0[e] * p2 + cw1[e] * p1 + cw2[e] * v[m][e];
;                             }
;                         } else {
;                             const int ns = rowb + 16 * m + fr - MP;
;                             f32x4 s0 = (f32x4){0.f, 0.f, 0.f, 0.f}, s1 = s0;
;                             if (ns < NS) {
;                                 s0 = *(const f32x4*)(state + (size_t)(ns * 2 + 0) * FF2 + oc); s1 = *(const f32x4*)(state + (size_t)(ns * 2 + 1) * FF2 + oc);
;                                 *(f32x4*)(ncs + (size_t)(ns * 2 + 0) * FF2 + oc) = s1; *(f32x4*)(ncs + (size_t)(ns * 2 + 1) * FF2 + oc) = v[m];
;                             }
;                             cv = cb + cw0 * s0 + cw1 * s1 + cw2 * v[m];
;                         }
;                         if (bj == 0) cg[m] = gelu4(cv);
;                         else {
;                             const f32x4 r = cg[m] * cv;
;                             v2u w; w.x = cvt_pk_bf16(r[0], r[1]); w.y = cvt_pk_bf16(r[2], r[3]);
;                             *(v2u*)(ACT + (size_t)(rowb + 16 * m + fr) * FF + 128 * u.pn + 32 * wc + 8 * fq + 4 * n) = w;
;                         }
	v_mov_b32_dpp v252, v106 row_shr:2 row_mask:0xf bank_mask:0xf
	v_mov_b32_dpp v249, v107 row_shr:1 row_mask:0xf bank_mask:0xf
	v_mov_b32_dpp v253, v107 row_shr:2 row_mask:0xf bank_mask:0xf
	v_pk_fma_f32 v[254:255], v[178:179], v[250:251], v[140:141]
	v_pk_fma_f32 v[148:149], v[180:181], v[252:253], v[142:143]
	v_pk_fma_f32 v[254:255], v[194:195], v[246:247], v[254:255]
	v_pk_fma_f32 v[148:149], v[196:197], v[248:249], v[148:149]
	v_pk_fma_f32 v[254:255], v[210:211], v[104:105], v[254:255]
	v_pk_fma_f32 v[148:149], v[212:213], v[106:107], v[148:149]
	v_pk_mul_f32 v[254:255], v[238:239], v[254:255]
	v_pk_mul_f32 v[148:149], v[240:241], v[148:149]
	v_cvt_pk_bf16_f32 v242, v254, v255
	v_cvt_pk_bf16_f32 v243, v148, v149
	v_mov_b32_dpp v246, v92 row_ror:1 row_mask:0xf bank_mask:0xf
	v_mov_b32_dpp v250, v92 row_ror:2 row_mask:0xf bank_mask:0xf
	v_mov_b32_dpp v247, v93 row_ror:1 row_mask:0xf bank_mask:0xf
	v_mov_b32_dpp v251, v93 row_ror:2 row_mask:0xf bank_mask:0xf
	v_mov_b32_dpp v248, v94 row_ror:1 row_mask:0xf bank_mask:0xf
	v_mov_b32_dpp v252, v94 row_ror:2 row_mask:0xf bank_mask:0xf
	v_mov_b32_dpp v249, v95 row_ror:1 row_mask:0xf bank_mask:0xf
	v_mov_b32_dpp v253, v95 row_ror:2 row_mask:0xf bank_mask:0xf
	v_mov_b32_dpp v246, v88 row_shr:1 row_mask:0xf bank_mask:0xf
	v_mov_b32_dpp v250, v88 row_shr:2 row_mask:0xf bank_mask:0xf
	v_mov_b32_dpp v247, v89 row_shr:1 row_mask:0xf bank_mask:0xf
	v_mov_b32_dpp v251, v89 row_shr:2 row_mask:0xf bank_mask:0xf
	v_mov_b32_dpp v248, v90 row_shr:1 row_mask:0xf bank_mask:0xf
	v_mov_b32_dpp v252, v90 row_shr:2 row_mask:0xf bank_mask:0xf
	v_mov_b32_dpp v249, v91 row_shr:1 row_mask:0xf bank_mask:0xf
	v_mov_b32_dpp v253, v91 row_shr:2 row_mask:0xf bank_mask:0xf
	v_pk_fma_f32 v[254:255], v[174:175], v[250:251], v[136:137]
	v_pk_fma_f32 v[148:149], v[176:177], v[252:253], v[138:139]
	v_pk_fma_f32 v[254:255], v[190:191], v[246:247], v[254:255]
	v_pk_fma_f32 v[148:149], v[192:193], v[248:249], v[148:149]
	v_pk_fma_f32 v[254:255], v[206:207], v[88:89], v[254:255]
	v_pk_fma_f32 v[148:149], v[208:209], v[90:91], v[148:149]
	v_and_b32_e32 v246, 0x7fffffff, v254
	v_and_b32_e32 v247, 0x7fffffff, v255
	v_and_b32_e32 v250, 0x7fffffff, v148
	v_and_b32_e32 v251, 0x7fffffff, v149
	v_pk_fma_f32 v[246:247], v[246:247], s[38:39], 1.0 op_sel_hi:[1,0,0]
	v_pk_fma_f32 v[250:251], v[250:251], s[38:39], 1.0 op_sel_hi:[1,0,0]
	v_pk_mul_f32 v[248:249], v[254:255], v[254:255]
	v_pk_mul_f32 v[252:253], v[148:149], v[148:149]
	v_rcp_f32_e32 v246, v246
	v_rcp_f32_e32 v247, v247
	v_rcp_f32_e32 v250, v250
	v_rcp_f32_e32 v251, v251
	v_pk_mul_f32 v[248:249], v[248:249], s[72:73] op_sel_hi:[1,0]
	v_pk_mul_f32 v[252:253], v[252:253], s[72:73] op_sel_hi:[1,0]
	v_mov_b64_e32 v[238:239], s[64:65]
	v_mov_b64_e32 v[240:241], s[64:65]
	v_exp_f32_e32 v248, v248
	v_exp_f32_e32 v249, v249
	v_exp_f32_e32 v252, v252
	v_exp_f32_e32 v253, v253
	v_pk_fma_f32 v[238:239], v[246:247], s[62:63], v[238:239] op_sel_hi:[1,0,0]
	v_pk_fma_f32 v[240:241], v[250:251], s[62:63], v[240:241] op_sel_hi:[1,0,0]
	v_pk_fma_f32 v[238:239], v[246:247], v[238:239], s[66:67] op_sel_hi:[1,1,0]
	v_pk_fma_f32 v[240:241], v[250:251], v[240:241], s[66:67] op_sel_hi:[1,1,0]
	v_pk_fma_f32 v[238:239], v[246:247], v[238:239], s[68:69] op_sel_hi:[1,1,0]
	v_pk_fma_f32 v[240:241], v[250:251], v[240:241], s[68:69] op_sel_hi:[1,1,0]
	v_pk_fma_f32 v[238:239], v[246:247], v[238:239], s[70:71] op_sel_hi:[1,1,0]
	v_pk_fma_f32 v[240:241], v[250:251], v[240:241], s[70:71] op_sel_hi:[1,1,0]
	v_pk_mul_f32 v[238:239], v[246:247], v[238:239]
	v_pk_mul_f32 v[240:241], v[250:251], v[240:241]
	v_pk_mul_f32 v[238:239], v[248:249], v[238:239]
	v_pk_mul_f32 v[240:241], v[252:253], v[240:241]
	v_cmp_gt_f32_e64 vcc, 0, v254
	v_cmp_gt_f32_e64 s[56:57], 0, v148
	v_cmp_gt_f32_e64 s[14:15], 0, v255
	v_cmp_gt_f32_e64 s[92:93], 0, v149
	v_pk_mul_f32 v[248:249], v[254:255], v[238:239]
	v_pk_mul_f32 v[252:253], v[148:149], v[240:241]
	v_pk_fma_f32 v[238:239], v[254:255], v[238:239], v[254:255] neg_lo:[1,0,0] neg_hi:[1,0,0]
	v_pk_fma_f32 v[240:241], v[148:149], v[240:241], v[148:149] neg_lo:[1,0,0] neg_hi:[1,0,0]
	v_cndmask_b32_e64 v238, v238, v248, vcc
	v_cndmask_b32_e64 v240, v240, v252, s[56:57]
	v_cndmask_b32_e64 v239, v239, v249, s[14:15]
	v_cndmask_b32_e64 v241, v241, v253, s[92:93]
	v_mov_b32_dpp v246, v76 row_ror:1 row_mask:0xf bank_mask:0xf
	v_mov_b32_dpp v250, v76 row_ror:2 row_mask:0xf bank_mask:0xf
	v_mov_b32_dpp v247, v77 row_ror:1 row_mask:0xf bank_mask:0xf
	v_mov_b32_dpp v251, v77 row_ror:2 row_mask:0xf bank_mask:0xf
	v_mov_b32_dpp v248, v78 row_ror:1 row_mask:0xf bank_mask:0xf
	v_mov_b32_dpp v252, v78 row_ror:2 row_mask:0xf bank_mask:0xf
	v_mov_b32_dpp v249, v79 row_ror:1 row_mask:0xf bank_mask:0xf
	v_mov_b32_dpp v253, v79 row_ror:2 row_mask:0xf bank_mask:0xf
	v_mov_b32_dpp v246, v72 row_shr:1 row_mask:0xf bank_mask:0xf
	v_mov_b32_dpp v250, v72 row_shr:2 row_mask:0xf bank_mask:0xf
	v_mov_b32_dpp v247, v73 row_shr:1 row_mask:0xf bank_mask:0xf
	v_mov_b32_dpp v251, v73 row_shr:2 row_mask:0xf bank_mask:0xf
	v_mov_b32_dpp v248, v74 row_shr:1 row_mask:0xf bank_mask:0xf
	v_mov_b32_dpp v252, v74 row_shr:2 row_mask:0xf bank_mask:0xf
	v_mov_b32_dpp v249, v75 row_shr:1 row_mask:0xf bank_mask:0xf
	v_mov_b32_dpp v253, v75 row_shr:2 row_mask:0xf bank_mask:0xf
	v_pk_fma_f32 v[254:255], v[182:183], v[250:251], v[144:145]
	v_pk_fma_f32 v[148:149], v[184:185], v[252:253], v[146:147]
	v_pk_fma_f32 v[254:255], v[198:199], v[246:247], v[254:255]
	v_pk_fma_f32 v[148:149], v[200:201], v[248:249], v[148:149]
	v_pk_fma_f32 v[254:255], v[128:129], v[72:73], v[254:255]
	v_pk_fma_f32 v[148:149], v[130:131], v[74:75], v[148:149]
; __device__ __forceinline__ f32x2 gelu_pk(f32x2 v) {
;     const f32x2 av = __builtin_elementwise_abs(v), d = av * 0.2316418882f + 1.0f;
;     __device__ __forceinline__ void operator()(const f32x4 (&acc)[2][2][4][2], const Unit& u, int wr, int wc, int fr, int fq) const {
;     ...
; #pragma unroll
;                     for (int m = 0; m < 4; ++m) {
;                         f32x4 cv;
;                         if (!samp) {
;                             const f32x4 prev = m ? v[m - 1] : hv;
; #pragma unroll
;                             for (int e = 0; e < 4; ++e) {
;                                 const int vi = __float_as_int(v[m][e]), pi = __float_as_int(prev[e]);
;                                 const int o1 = __builtin_amdgcn_mov_dpp(pi, 0x121, 0xf, 0xf, false);
;                                 const int o2 = __builtin_amdgcn_mov_dpp(pi, 0x122, 0xf, 0xf, false);
;                                 const float p1 = __int_as_float(__builtin_amdgcn_update_dpp(o1, vi, 0x111, 0xf, 0xf, false));
;                                 const float p2 = __int_as_float(__builtin_amdgcn_update_dpp(o2, vi, 0x112, 0xf, 0xf, false));
;                                 cv[e] = cb[e] + cw0[e] * p2 + cw1[e] * p1 + cw2[e] * v[m][e];
;                             }
;                         } else {
;                             const int ns = rowb + 16 * m + fr - MP;
;                             f32x4 s0 = (f32x4){0.f, 0.f, 0.f, 0.f}, s1 = s0;
;                             if (ns < NS) {
;                                 s0 = *(const f32x4*)(state + (size_t)(ns * 2 + 0) * FF2 + oc); s1 = *(const f32x4*)(state + (size_t)(ns * 2 + 1) * FF2 + oc);
;                                 *(f32x4*)(ncs + (size_t)(ns * 2 + 0) * FF2 + oc) = s1; *(f32x4*)(ncs + (size_t)(ns * 2 + 1) * FF2 + oc) = v[m];
;                             }
;                             cv = cb + cw0 * s0 + cw1 * s1 + cw2 * v[m];
;                         }
;                         if (bj == 0) cg[m] = gelu4(cv);
;                         else {
;                             const f32x4 r = cg[m] * cv;
;                             v2u w; w.x = cvt_pk_bf16(r[0], r[1]); w.y = cvt_pk_bf16(r[2], r[3]);
;                             *(v2u*)(ACT + (size_t)(rowb + 16 * m + fr) * FF + 128 * u.pn + 32 * wc + 8 * fq + 4 * n) = w;
;                         }
	v_pk_mul_f32 v[254:255], v[238:239], v[254:255]
	v_pk_mul_f32 v[148:149], v[240:241], v[148:149]
	v_cvt_pk_bf16_f32 v244, v254, v255
	v_cvt_pk_bf16_f32 v245, v148, v149
	s_add_u32 s56, s46, 0x16000
	s_addc_u32 s57, s47, 0
	global_store_dwordx4 v151, v[242:245], s[56:57]
	v_mov_b32_dpp v246, v120 row_ror:1 row_mask:0xf bank_mask:0xf
	v_mov_b32_dpp v250, v120 row_ror:2 row_mask:0xf bank_mask:0xf
	v_mov_b32_dpp v247, v121 row_ror:1 row_mask:0xf bank_mask:0xf
	v_mov_b32_dpp v251, v121 row_ror:2 row_mask:0xf bank_mask:0xf
	v_mov_b32_dpp v248, v122 row_ror:1 row_mask:0xf bank_mask:0xf
	v_mov_b32_dpp v252, v122 row_ror:2 row_mask:0xf bank_mask:0xf
	v_mov_b32_dpp v249, v123 row_ror:1 row_mask:0xf bank_mask:0xf
	v_mov_b32_dpp v253, v123 row_ror:2 row_mask:0xf bank_mask:0xf
	v_mov_b32_dpp v246, v116 row_shr:1 row_mask:0xf bank_mask:0xf
	v_mov_b32_dpp v250, v116 row_shr:2 row_mask:0xf bank_mask:0xf
	v_mov_b32_dpp v247, v117 row_shr:1 row_mask:0xf bank_mask:0xf
	v_mov_b32_dpp v251, v117 row_shr:2 row_mask:0xf bank_mask:0xf
	v_mov_b32_dpp v248, v118 row_shr:1 row_mask:0xf bank_mask:0xf
	v_mov_b32_dpp v252, v118 row_shr:2 row_mask:0xf bank_mask:0xf
	v_mov_b32_dpp v249, v119 row_shr:1 row_mask:0xf bank_mask:0xf
	v_mov_b32_dpp v253, v119 row_shr:2 row_mask:0xf bank_mask:0xf
	v_pk_fma_f32 v[254:255], v[170:171], v[250:251], v[132:133]
	v_pk_fma_f32 v[148:149], v[172:173], v[252:253], v[134:135]
	v_pk_fma_f32 v[254:255], v[186:187], v[246:247], v[254:255]
	v_pk_fma_f32 v[148:149], v[188:189], v[248:249], v[148:149]
	v_pk_fma_f32 v[254:255], v[202:203], v[116:117], v[254:255]
	v_pk_fma_f32 v[148:149], v[204:205], v[118:119], v[148:149]
	v_and_b32_e32 v246, 0x7fffffff, v254
	v_and_b32_e32 v247, 0x7fffffff, v255
	v_and_b32_e32 v250, 0x7fffffff, v148
	v_and_b32_e32 v251, 0x7fffffff, v149
	v_pk_fma_f32 v[246:247], v[246:247], s[38:39], 1.0 op_sel_hi:[1,0,0]
	v_pk_fma_f32 v[250:251], v[250:251], s[38:39], 1.0 op_sel_hi:[1,0,0]
	v_pk_mul_f32 v[248:249], v[254:255], v[254:255]
	v_pk_mul_f32 v[252:253], v[148:149], v[148:149]
	v_rcp_f32_e32 v246, v246
	v_rcp_f32_e32 v247, v247
	v_rcp_f32_e32 v250, v250
	v_rcp_f32_e32 v251, v251
	v_pk_mul_f32 v[248:249], v[248:249], s[72:73] op_sel_hi:[1,0]
	v_pk_mul_f32 v[252:253], v[252:253], s[72:73] op_sel_hi:[1,0]
	v_mov_b64_e32 v[238:239], s[64:65]
	v_mov_b64_e32 v[240:241], s[64:65]
	v_exp_f32_e32 v248, v248
	v_exp_f32_e32 v249, v249
	v_exp_f32_e32 v252, v252
	v_exp_f32_e32 v253, v253
	v_pk_fma_f32 v[238:239], v[246:247], s[62:63], v[238:239] op_sel_hi:[1,0,0]
	v_pk_fma_f32 v[240:241], v[250:251], s[62:63], v[240:241] op_sel_hi:[1,0,0]
	v_pk_fma_f32 v[238:239], v[246:247], v[238:239], s[66:67] op_sel_hi:[1,1,0]
	v_pk_fma_f32 v[240:241], v[250:251], v[240:241], s[66:67] op_sel_hi:[1,1,0]
	v_pk_fma_f32 v[238:239], v[246:247], v[238:239], s[68:69] op_sel_hi:[1,1,0]
	v_pk_fma_f32 v[240:241], v[250:251], v[240:241], s[68:69] op_sel_hi:[1,1,0]
	v_pk_fma_f32 v[238:239], v[246:247], v[238:239], s[70:71] op_sel_hi:[1,1,0]
	v_pk_fma_f32 v[240:241], v[250:251], v[240:241], s[70:71] op_sel_hi:[1,1,0]
	v_pk_mul_f32 v[238:239], v[246:247], v[238:239]
	v_pk_mul_f32 v[240:241], v[250:251], v[240:241]
	v_pk_mul_f32 v[238:239], v[248:249], v[238:239]
	v_pk_mul_f32 v[240:241], v[252:253], v[240:241]
	v_cmp_gt_f32_e64 vcc, 0, v254
	v_cmp_gt_f32_e64 s[56:57], 0, v148
	v_cmp_gt_f32_e64 s[14:15], 0, v255
	v_cmp_gt_f32_e64 s[92:93], 0, v149
	v_pk_mul_f32 v[248:249], v[254:255], v[238:239]
	v_pk_mul_f32 v[252:253], v[148:149], v[240:241]
	v_pk_fma_f32 v[238:239], v[254:255], v[238:239], v[254:255] neg_lo:[1,0,0] neg_hi:[1,0,0]
	v_pk_fma_f32 v[240:241], v[148:149], v[240:241], v[148:149] neg_lo:[1,0,0] neg_hi:[1,0,0]
	v_cndmask_b32_e64 v238, v238, v248, vcc
	v_cndmask_b32_e64 v240, v240, v252, s[56:57]
	v_cndmask_b32_e64 v239, v239, v249, s[14:15]
	v_cndmask_b32_e64 v241, v241, v253, s[92:93]
	v_mov_b32_dpp v246, v104 row_ror:1 row_mask:0xf bank_mask:0xf
	v_mov_b32_dpp v250, v104 row_ror:2 row_mask:0xf bank_mask:0xf
	v_mov_b32_dpp v247, v105 row_ror:1 row_mask:0xf bank_mask:0xf
	v_mov_b32_dpp v251, v105 row_ror:2 row_mask:0xf bank_mask:0xf
	v_mov_b32_dpp v248, v106 row_ror:1 row_mask:0xf bank_mask:0xf
	v_mov_b32_dpp v252, v106 row_ror:2 row_mask:0xf bank_mask:0xf
	v_mov_b32_dpp v249, v107 row_ror:1 row_mask:0xf bank_mask:0xf
	v_mov_b32_dpp v253, v107 row_ror:2 row_mask:0xf bank_mask:0xf
	v_mov_b32_dpp v246, v100 row_shr:1 row_mask:0xf bank_mask:0xf
	v_mov_b32_dpp v250, v100 row_shr:2 row_mask:0xf bank_mask:0xf
	v_mov_b32_dpp v247, v101 row_shr:1 row_mask:0xf bank_mask:0xf
	v_mov_b32_dpp v251, v101 row_shr:2 row_mask:0xf bank_mask:0xf
	v_mov_b32_dpp v248, v102 row_shr:1 row_mask:0xf bank_mask:0xf
	v_mov_b32_dpp v252, v102 row_shr:2 row_mask:0xf bank_mask:0xf
	v_mov_b32_dpp v249, v103 row_shr:1 row_mask:0xf bank_mask:0xf
	v_mov_b32_dpp v253, v103 row_shr:2 row_mask:0xf bank_mask:0xf
	v_pk_fma_f32 v[254:255], v[178:179], v[250:251], v[140:141]
	v_pk_fma_f32 v[148:149], v[180:181], v[252:253], v[142:143]
	v_pk_fma_f32 v[254:255], v[194:195], v[246:247], v[254:255]
	v_pk_fma_f32 v[148:149], v[196:197], v[248:249], v[148:149]
	v_pk_fma_f32 v[254:255], v[210:211], v[100:101], v[254:255]
	v_pk_fma_f32 v[148:149], v[212:213], v[102:103], v[148:149]
	v_pk_mul_f32 v[254:255], v[238:239], v[254:255]
	v_pk_mul_f32 v[148:149], v[240:241], v[148:149]
	v_cvt_pk_bf16_f32 v242, v254, v255
	v_cvt_pk_bf16_f32 v243, v148, v149
	v_mov_b32_dpp v246, v88 row_ror:1 row_mask:0xf bank_mask:0xf
	v_mov_b32_dpp v250, v88 row_ror:2 row_mask:0xf bank_mask:0xf
	v_mov_b32_dpp v247, v89 row_ror:1 row_mask:0xf bank_mask:0xf
	v_mov_b32_dpp v251, v89 row_ror:2 row_mask:0xf bank_mask:0xf
; __device__ __forceinline__ f32x2 gelu_pk(f32x2 v) {
;     const f32x2 av = __builtin_elementwise_abs(v), d = av * 0.2316418882f + 1.0f;
;     __device__ __forceinline__ void operator()(const f32x4 (&acc)[2][2][4][2], const Unit& u, int wr, int wc, int fr, int fq) const {
;     ...
; #pragma unroll
;                     for (int m = 0; m < 4; ++m) {
;                         f32x4 cv;
;                         if (!samp) {
;                             const f32x4 prev = m ? v[m - 1] : hv;
; #pragma unroll
;                             for (int e = 0; e < 4; ++e) {
;                                 const int vi = __float_as_int(v[m][e]), pi = __float_as_int(prev[e]);
;                                 const int o1 = __builtin_amdgcn_mov_dpp(pi, 0x121, 0xf, 0xf, false);
;                                 const int o2 = __builtin_amdgcn_mov_dpp(pi, 0x122, 0xf, 0xf, false);
;                                 const float p1 = __int_as_float(__builtin_amdgcn_update_dpp(o1, vi, 0x111, 0xf, 0xf, false));
;                                 const float p2 = __int_as_float(__builtin_amdgcn_update_dpp(o2, vi, 0x112, 0xf, 0xf, false));
;                                 cv[e] = cb[e] + cw0[e] * p2 + cw1[e] * p1 + cw2[e] * v[m][e];
;                             }
;                         } else {
;                             const int ns = rowb + 16 * m + fr - MP;
;                             f32x4 s0 = (f32x4){0.f, 0.f, 0.f, 0.f}, s1 = s0;
;                             if (ns < NS) {
;                                 s0 = *(const f32x4*)(state + (size_t)(ns * 2 + 0) * FF2 + oc); s1 = *(const f32x4*)(state + (size_t)(ns * 2 + 1) * FF2 + oc);
;                                 *(f32x4*)(ncs + (size_t)(ns * 2 + 0) * FF2 + oc) = s1; *(f32x4*)(ncs + (size_t)(ns * 2 + 1) * FF2 + oc) = v[m];
;                             }
;                             cv = cb + cw0 * s0 + cw1 * s1 + cw2 * v[m];
;                         }
;                         if (bj == 0) cg[m] = gelu4(cv);
;                         else {
;                             const f32x4 r = cg[m] * cv;
;                             v2u w; w.x = cvt_pk_bf16(r[0], r[1]); w.y = cvt_pk_bf16(r[2], r[3]);
;                             *(v2u*)(ACT + (size_t)(rowb + 16 * m + fr) * FF + 128 * u.pn + 32 * wc + 8 * fq + 4 * n) = w;
;                         }
	v_mov_b32_dpp v248, v90 row_ror:1 row_mask:0xf bank_mask:0xf
	v_mov_b32_dpp v252, v90 row_ror:2 row_mask:0xf bank_mask:0xf
	v_mov_b32_dpp v249, v91 row_ror:1 row_mask:0xf bank_mask:0xf
	v_mov_b32_dpp v253, v91 row_ror:2 row_mask:0xf bank_mask:0xf
	v_mov_b32_dpp v246, v84 row_shr:1 row_mask:0xf bank_mask:0xf
	v_mov_b32_dpp v250, v84 row_shr:2 row_mask:0xf bank_mask:0xf
	v_mov_b32_dpp v247, v85 row_shr:1 row_mask:0xf bank_mask:0xf
	v_mov_b32_dpp v251, v85 row_shr:2 row_mask:0xf bank_mask:0xf
	v_mov_b32_dpp v248, v86 row_shr:1 row_mask:0xf bank_mask:0xf
	v_mov_b32_dpp v252, v86 row_shr:2 row_mask:0xf bank_mask:0xf
	v_mov_b32_dpp v249, v87 row_shr:1 row_mask:0xf bank_mask:0xf
	v_mov_b32_dpp v253, v87 row_shr:2 row_mask:0xf bank_mask:0xf
	v_pk_fma_f32 v[254:255], v[174:175], v[250:251], v[136:137]
	v_pk_fma_f32 v[148:149], v[176:177], v[252:253], v[138:139]
	v_pk_fma_f32 v[254:255], v[190:191], v[246:247], v[254:255]
	v_pk_fma_f32 v[148:149], v[192:193], v[248:249], v[148:149]
	v_pk_fma_f32 v[254:255], v[206:207], v[84:85], v[254:255]
	v_pk_fma_f32 v[148:149], v[208:209], v[86:87], v[148:149]
	v_and_b32_e32 v246, 0x7fffffff, v254
	v_and_b32_e32 v247, 0x7fffffff, v255
	v_and_b32_e32 v250, 0x7fffffff, v148
	v_and_b32_e32 v251, 0x7fffffff, v149
	v_pk_fma_f32 v[246:247], v[246:247], s[38:39], 1.0 op_sel_hi:[1,0,0]
	v_pk_fma_f32 v[250:251], v[250:251], s[38:39], 1.0 op_sel_hi:[1,0,0]
	v_pk_mul_f32 v[248:249], v[254:255], v[254:255]
	v_pk_mul_f32 v[252:253], v[148:149], v[148:149]
	v_rcp_f32_e32 v246, v246
	v_rcp_f32_e32 v247, v247
	v_rcp_f32_e32 v250, v250
	v_rcp_f32_e32 v251, v251
	v_pk_mul_f32 v[248:249], v[248:249], s[72:73] op_sel_hi:[1,0]
	v_pk_mul_f32 v[252:253], v[252:253], s[72:73] op_sel_hi:[1,0]
	v_mov_b64_e32 v[238:239], s[64:65]
	v_mov_b64_e32 v[240:241], s[64:65]
	v_exp_f32_e32 v248, v248
	v_exp_f32_e32 v249, v249
	v_exp_f32_e32 v252, v252
	v_exp_f32_e32 v253, v253
	v_pk_fma_f32 v[238:239], v[246:247], s[62:63], v[238:239] op_sel_hi:[1,0,0]
	v_pk_fma_f32 v[240:241], v[250:251], s[62:63], v[240:241] op_sel_hi:[1,0,0]
	v_pk_fma_f32 v[238:239], v[246:247], v[238:239], s[66:67] op_sel_hi:[1,1,0]
	v_pk_fma_f32 v[240:241], v[250:251], v[240:241], s[66:67] op_sel_hi:[1,1,0]
	v_pk_fma_f32 v[238:239], v[246:247], v[238:239], s[68:69] op_sel_hi:[1,1,0]
	v_pk_fma_f32 v[240:241], v[250:251], v[240:241], s[68:69] op_sel_hi:[1,1,0]
	v_pk_fma_f32 v[238:239], v[246:247], v[238:239], s[70:71] op_sel_hi:[1,1,0]
	v_pk_fma_f32 v[240:241], v[250:251], v[240:241], s[70:71] op_sel_hi:[1,1,0]
	v_pk_mul_f32 v[238:239], v[246:247], v[238:239]
	v_pk_mul_f32 v[240:241], v[250:251], v[240:241]
	v_pk_mul_f32 v[238:239], v[248:249], v[238:239]
	v_pk_mul_f32 v[240:241], v[252:253], v[240:241]
	v_cmp_gt_f32_e64 vcc, 0, v254
	v_cmp_gt_f32_e64 s[56:57], 0, v148
	v_cmp_gt_f32_e64 s[14:15], 0, v255
	v_cmp_gt_f32_e64 s[92:93], 0, v149
	v_pk_mul_f32 v[248:249], v[254:255], v[238:239]
	v_pk_mul_f32 v[252:253], v[148:149], v[240:241]
	v_pk_fma_f32 v[238:239], v[254:255], v[238:239], v[254:255] neg_lo:[1,0,0] neg_hi:[1,0,0]
	v_pk_fma_f32 v[240:241], v[148:149], v[240:241], v[148:149] neg_lo:[1,0,0] neg_hi:[1,0,0]
	v_cndmask_b32_e64 v238, v238, v248, vcc
	v_cndmask_b32_e64 v240, v240, v252, s[56:57]
	v_cndmask_b32_e64 v239, v239, v249, s[14:15]
	v_cndmask_b32_e64 v241, v241, v253, s[92:93]
	v_mov_b32_dpp v246, v72 row_ror:1 row_mask:0xf bank_mask:0xf
	v_mov_b32_dpp v250, v72 row_ror:2 row_mask:0xf bank_mask:0xf
	v_mov_b32_dpp v247, v73 row_ror:1 row_mask:0xf bank_mask:0xf
	v_mov_b32_dpp v251, v73 row_ror:2 row_mask:0xf bank_mask:0xf
	v_mov_b32_dpp v248, v74 row_ror:1 row_mask:0xf bank_mask:0xf
	v_mov_b32_dpp v252, v74 row_ror:2 row_mask:0xf bank_mask:0xf
	v_mov_b32_dpp v249, v75 row_ror:1 row_mask:0xf bank_mask:0xf
	v_mov_b32_dpp v253, v75 row_ror:2 row_mask:0xf bank_mask:0xf
	v_mov_b32_dpp v246, v68 row_shr:1 row_mask:0xf bank_mask:0xf
	v_mov_b32_dpp v250, v68 row_shr:2 row_mask:0xf bank_mask:0xf
	v_mov_b32_dpp v247, v69 row_shr:1 row_mask:0xf bank_mask:0xf
	v_mov_b32_dpp v251, v69 row_shr:2 row_mask:0xf bank_mask:0xf
	v_mov_b32_dpp v248, v70 row_shr:1 row_mask:0xf bank_mask:0xf
	v_mov_b32_dpp v252, v70 row_shr:2 row_mask:0xf bank_mask:0xf
	v_mov_b32_dpp v249, v71 row_shr:1 row_mask:0xf bank_mask:0xf
	v_mov_b32_dpp v253, v71 row_shr:2 row_mask:0xf bank_mask:0xf
	v_pk_fma_f32 v[254:255], v[182:183], v[250:251], v[144:145]
	v_pk_fma_f32 v[148:149], v[184:185], v[252:253], v[146:147]
	v_pk_fma_f32 v[254:255], v[198:199], v[246:247], v[254:255]
	v_pk_fma_f32 v[148:149], v[200:201], v[248:249], v[148:149]
	v_pk_fma_f32 v[254:255], v[128:129], v[68:69], v[254:255]
	v_pk_fma_f32 v[148:149], v[130:131], v[70:71], v[148:149]
	v_pk_mul_f32 v[254:255], v[238:239], v[254:255]
	v_pk_mul_f32 v[148:149], v[240:241], v[148:149]
	v_cvt_pk_bf16_f32 v244, v254, v255
	v_cvt_pk_bf16_f32 v245, v148, v149
	s_add_u32 s56, s46, 0x2c000
	s_addc_u32 s57, s47, 0
	global_store_dwordx4 v151, v[242:245], s[56:57]
	v_mov_b32_dpp v246, v116 row_ror:1 row_mask:0xf bank_mask:0xf
	v_mov_b32_dpp v250, v116 row_ror:2 row_mask:0xf bank_mask:0xf
	v_mov_b32_dpp v247, v117 row_ror:1 row_mask:0xf bank_mask:0xf
	v_mov_b32_dpp v251, v117 row_ror:2 row_mask:0xf bank_mask:0xf
	v_mov_b32_dpp v248, v118 row_ror:1 row_mask:0xf bank_mask:0xf
	v_mov_b32_dpp v252, v118 row_ror:2 row_mask:0xf bank_mask:0xf
	v_mov_b32_dpp v249, v119 row_ror:1 row_mask:0xf bank_mask:0xf
	v_mov_b32_dpp v253, v119 row_ror:2 row_mask:0xf bank_mask:0xf
	v_mov_b32_dpp v246, v112 row_shr:1 row_mask:0xf bank_mask:0xf
	v_mov_b32_dpp v250, v112 row_shr:2 row_mask:0xf bank_mask:0xf
	v_mov_b32_dpp v247, v113 row_shr:1 row_mask:0xf bank_mask:0xf
;     __device__ __forceinline__ void operator()(const f32x4 (&acc)[2][2][4][2], const Unit& u, int wr, int wc, int fr, int fq) const {
;     ...
;                     const int oc = (bj ? FF : 0) + 128 * u.pn + 32 * wc + 8 * fq + 4 * n;
;                     const int cgc = 256 * u.pn + 128 * bj + 32 * wc + 8 * fq + 4 * n;
;                     const f32x4 cw0 = *(const f32x4*)(convw + oc), cw1 = *(const f32x4*)(convw + FF2 + oc), cw2 = *(const f32x4*)(convw + 2 * FF2 + oc), cb = *(const f32x4*)(convb + oc);
;                     f32x4 v[4];
; #pragma unroll
;                     for (int m = 0; m < 4; ++m) v[m] = acc[ai][bj][m][n] * rs[m];
;                     f32x4 hv = (f32x4){0.f, 0.f, 0.f, 0.f};
;                     if (!samp) {
;                         if ((blk & 31) != 0 && fr >= 14) hv = *(const f32x4*)(HALO + (size_t)(2 * blk + fr - 14) * FF2 + cgc);
;                         if ((u.pm & 7) == 7 && ai == 1 && wr == 1 && fr >= 14) *(f32x4*)(ncp + (size_t)((u.pm >> 3) * 2 + (fr - 14)) * FF2 + oc) = v[3];
;                     }
; #pragma unroll
;                     for (int m = 0; m < 4; ++m) {
;                         f32x4 cv;
;                         if (!samp) {
;                             const f32x4 prev = m ? v[m - 1] : hv;
; #pragma unroll
;                             for (int e = 0; e < 4; ++e) {
;                                 const int vi = __float_as_int(v[m][e]), pi = __float_as_int(prev[e]);
;                                 const int o1 = __builtin_amdgcn_mov_dpp(pi, 0x121, 0xf, 0xf, false);
;                                 const int o2 = __builtin_amdgcn_mov_dpp(pi, 0x122, 0xf, 0xf, false);
;                                 const float p1 = __int_as_float(__builtin_amdgcn_update_dpp(o1, vi, 0x111, 0xf, 0xf, false));
;                                 const float p2 = __int_as_float(__builtin_amdgcn_update_dpp(o2, vi, 0x112, 0xf, 0xf, false));
;                                 cv[e] = cb[e] + cw0[e] * p2 + cw1[e] * p1 + cw2[e] * v[m][e];
;                             }
;                         } else {
;                             const int ns = rowb + 16 * m + fr - MP;
;                             f32x4 s0 = (f32x4){0.f, 0.f, 0.f, 0.f}, s1 = s0;
;                             if (ns < NS) {
	v_mov_b32_dpp v251, v113 row_shr:2 row_mask:0xf bank_mask:0xf
	v_mov_b32_dpp v248, v114 row_shr:1 row_mask:0xf bank_mask:0xf
	v_mov_b32_dpp v252, v114 row_shr:2 row_mask:0xf bank_mask:0xf
	v_mov_b32_dpp v249, v115 row_shr:1 row_mask:0xf bank_mask:0xf
	v_mov_b32_dpp v253, v115 row_shr:2 row_mask:0xf bank_mask:0xf
	v_pk_fma_f32 v[254:255], v[170:171], v[250:251], v[132:133]
	v_pk_fma_f32 v[148:149], v[172:173], v[252:253], v[134:135]
	v_pk_fma_f32 v[254:255], v[186:187], v[246:247], v[254:255]
	v_pk_fma_f32 v[148:149], v[188:189], v[248:249], v[148:149]
	v_pk_fma_f32 v[254:255], v[202:203], v[112:113], v[254:255]
	v_pk_fma_f32 v[148:149], v[204:205], v[114:115], v[148:149]
	v_and_b32_e32 v246, 0x7fffffff, v254
	v_and_b32_e32 v247, 0x7fffffff, v255
	v_and_b32_e32 v250, 0x7fffffff, v148
	v_and_b32_e32 v251, 0x7fffffff, v149
	v_pk_fma_f32 v[246:247], v[246:247], s[38:39], 1.0 op_sel_hi:[1,0,0]
	v_pk_fma_f32 v[250:251], v[250:251], s[38:39], 1.0 op_sel_hi:[1,0,0]
	v_pk_mul_f32 v[248:249], v[254:255], v[254:255]
	v_pk_mul_f32 v[252:253], v[148:149], v[148:149]
	v_rcp_f32_e32 v246, v246
	v_rcp_f32_e32 v247, v247
	v_rcp_f32_e32 v250, v250
	v_rcp_f32_e32 v251, v251
	v_pk_mul_f32 v[248:249], v[248:249], s[72:73] op_sel_hi:[1,0]
	v_pk_mul_f32 v[252:253], v[252:253], s[72:73] op_sel_hi:[1,0]
	v_mov_b64_e32 v[238:239], s[64:65]
	v_mov_b64_e32 v[240:241], s[64:65]
	v_exp_f32_e32 v248, v248
	v_exp_f32_e32 v249, v249
	v_exp_f32_e32 v252, v252
	v_exp_f32_e32 v253, v253
	v_pk_fma_f32 v[238:239], v[246:247], s[62:63], v[238:239] op_sel_hi:[1,0,0]
	v_pk_fma_f32 v[240:241], v[250:251], s[62:63], v[240:241] op_sel_hi:[1,0,0]
	v_pk_fma_f32 v[238:239], v[246:247], v[238:239], s[66:67] op_sel_hi:[1,1,0]
	v_pk_fma_f32 v[240:241], v[250:251], v[240:241], s[66:67] op_sel_hi:[1,1,0]
	v_pk_fma_f32 v[238:239], v[246:247], v[238:239], s[68:69] op_sel_hi:[1,1,0]
	v_pk_fma_f32 v[240:241], v[250:251], v[240:241], s[68:69] op_sel_hi:[1,1,0]
	v_pk_fma_f32 v[238:239], v[246:247], v[238:239], s[70:71] op_sel_hi:[1,1,0]
	v_pk_fma_f32 v[240:241], v[250:251], v[240:241], s[70:71] op_sel_hi:[1,1,0]
	v_pk_mul_f32 v[238:239], v[246:247], v[238:239]
	v_pk_mul_f32 v[240:241], v[250:251], v[240:241]
	v_pk_mul_f32 v[238:239], v[248:249], v[238:239]
	v_pk_mul_f32 v[240:241], v[252:253], v[240:241]
	v_cmp_gt_f32_e64 vcc, 0, v254
	v_cmp_gt_f32_e64 s[56:57], 0, v148
	v_cmp_gt_f32_e64 s[14:15], 0, v255
	v_cmp_gt_f32_e64 s[92:93], 0, v149
	v_pk_mul_f32 v[248:249], v[254:255], v[238:239]
	v_pk_mul_f32 v[252:253], v[148:149], v[240:241]
	v_pk_fma_f32 v[238:239], v[254:255], v[238:239], v[254:255] neg_lo:[1,0,0] neg_hi:[1,0,0]
	v_pk_fma_f32 v[240:241], v[148:149], v[240:241], v[148:149] neg_lo:[1,0,0] neg_hi:[1,0,0]
	v_cndmask_b32_e64 v238, v238, v248, vcc
	v_cndmask_b32_e64 v240, v240, v252, s[56:57]
	v_cndmask_b32_e64 v239, v239, v249, s[14:15]
	v_cndmask_b32_e64 v241, v241, v253, s[92:93]
	v_mov_b32_dpp v246, v100 row_ror:1 row_mask:0xf bank_mask:0xf
	v_mov_b32_dpp v250, v100 row_ror:2 row_mask:0xf bank_mask:0xf
	v_mov_b32_dpp v247, v101 row_ror:1 row_mask:0xf bank_mask:0xf
	v_mov_b32_dpp v251, v101 row_ror:2 row_mask:0xf bank_mask:0xf
	v_mov_b32_dpp v248, v102 row_ror:1 row_mask:0xf bank_mask:0xf
	v_mov_b32_dpp v252, v102 row_ror:2 row_mask:0xf bank_mask:0xf
	v_mov_b32_dpp v249, v103 row_ror:1 row_mask:0xf bank_mask:0xf
	v_mov_b32_dpp v253, v103 row_ror:2 row_mask:0xf bank_mask:0xf
	v_mov_b32_dpp v246, v96 row_shr:1 row_mask:0xf bank_mask:0xf
	v_mov_b32_dpp v250, v96 row_shr:2 row_mask:0xf bank_mask:0xf
	v_mov_b32_dpp v247, v97 row_shr:1 row_mask:0xf bank_mask:0xf
	v_mov_b32_dpp v251, v97 row_shr:2 row_mask:0xf bank_mask:0xf
	v_mov_b32_dpp v248, v98 row_shr:1 row_mask:0xf bank_mask:0xf
	v_mov_b32_dpp v252, v98 row_shr:2 row_mask:0xf bank_mask:0xf
	v_mov_b32_dpp v249, v99 row_shr:1 row_mask:0xf bank_mask:0xf
	v_mov_b32_dpp v253, v99 row_shr:2 row_mask:0xf bank_mask:0xf
	v_pk_fma_f32 v[254:255], v[178:179], v[250:251], v[140:141]
	v_pk_fma_f32 v[148:149], v[180:181], v[252:253], v[142:143]
	v_pk_fma_f32 v[254:255], v[194:195], v[246:247], v[254:255]
	v_pk_fma_f32 v[148:149], v[196:197], v[248:249], v[148:149]
	v_pk_fma_f32 v[254:255], v[210:211], v[96:97], v[254:255]
	v_pk_fma_f32 v[148:149], v[212:213], v[98:99], v[148:149]
	v_pk_mul_f32 v[254:255], v[238:239], v[254:255]
	v_pk_mul_f32 v[148:149], v[240:241], v[148:149]
	v_cvt_pk_bf16_f32 v242, v254, v255
	v_cvt_pk_bf16_f32 v243, v148, v149
	v_mov_b32_dpp v246, v84 row_ror:1 row_mask:0xf bank_mask:0xf
	v_mov_b32_dpp v250, v84 row_ror:2 row_mask:0xf bank_mask:0xf
	v_mov_b32_dpp v247, v85 row_ror:1 row_mask:0xf bank_mask:0xf
	v_mov_b32_dpp v251, v85 row_ror:2 row_mask:0xf bank_mask:0xf
	v_mov_b32_dpp v248, v86 row_ror:1 row_mask:0xf bank_mask:0xf
	v_mov_b32_dpp v252, v86 row_ror:2 row_mask:0xf bank_mask:0xf
	v_mov_b32_dpp v249, v87 row_ror:1 row_mask:0xf bank_mask:0xf
	v_mov_b32_dpp v253, v87 row_ror:2 row_mask:0xf bank_mask:0xf
	v_mov_b32_dpp v246, v80 row_shr:1 row_mask:0xf bank_mask:0xf
	v_mov_b32_dpp v250, v80 row_shr:2 row_mask:0xf bank_mask:0xf
	v_mov_b32_dpp v247, v81 row_shr:1 row_mask:0xf bank_mask:0xf
	v_mov_b32_dpp v251, v81 row_shr:2 row_mask:0xf bank_mask:0xf
	v_mov_b32_dpp v248, v82 row_shr:1 row_mask:0xf bank_mask:0xf
	v_mov_b32_dpp v252, v82 row_shr:2 row_mask:0xf bank_mask:0xf
	v_mov_b32_dpp v249, v83 row_shr:1 row_mask:0xf bank_mask:0xf
	v_mov_b32_dpp v253, v83 row_shr:2 row_mask:0xf bank_mask:0xf
	v_pk_fma_f32 v[254:255], v[174:175], v[250:251], v[136:137]
	v_pk_fma_f32 v[148:149], v[176:177], v[252:253], v[138:139]
	v_pk_fma_f32 v[254:255], v[190:191], v[246:247], v[254:255]
	v_pk_fma_f32 v[148:149], v[192:193], v[248:249], v[148:149]
; __device__ __forceinline__ f32x2 gelu_pk(f32x2 v) {
;     const f32x2 av = __builtin_elementwise_abs(v), d = av * 0.2316418882f + 1.0f;
;     __device__ __forceinline__ void operator()(const f32x4 (&acc)[2][2][4][2], const Unit& u, int wr, int wc, int fr, int fq) const {
;     ...
; #pragma unroll
;                     for (int m = 0; m < 4; ++m) {
;                         f32x4 cv;
;                         if (!samp) {
;                             const f32x4 prev = m ? v[m - 1] : hv;
; #pragma unroll
;                             for (int e = 0; e < 4; ++e) {
;                                 const int vi = __float_as_int(v[m][e]), pi = __float_as_int(prev[e]);
;                                 const int o1 = __builtin_amdgcn_mov_dpp(pi, 0x121, 0xf, 0xf, false);
;                                 const int o2 = __builtin_amdgcn_mov_dpp(pi, 0x122, 0xf, 0xf, false);
;                                 const float p1 = __int_as_float(__builtin_amdgcn_update_dpp(o1, vi, 0x111, 0xf, 0xf, false));
;                                 const float p2 = __int_as_float(__builtin_amdgcn_update_dpp(o2, vi, 0x112, 0xf, 0xf, false));
;                                 cv[e] = cb[e] + cw0[e] * p2 + cw1[e] * p1 + cw2[e] * v[m][e];
;                             }
;                         } else {
;                             const int ns = rowb + 16 * m + fr - MP;
;                             f32x4 s0 = (f32x4){0.f, 0.f, 0.f, 0.f}, s1 = s0;
;                             if (ns < NS) {
;                                 s0 = *(const f32x4*)(state + (size_t)(ns * 2 + 0) * FF2 + oc); s1 = *(const f32x4*)(state + (size_t)(ns * 2 + 1) * FF2 + oc);
;                                 *(f32x4*)(ncs + (size_t)(ns * 2 + 0) * FF2 + oc) = s1; *(f32x4*)(ncs + (size_t)(ns * 2 + 1) * FF2 + oc) = v[m];
;                             }
;                             cv = cb + cw0 * s0 + cw1 * s1 + cw2 * v[m];
;                         }
;                         if (bj == 0) cg[m] = gelu4(cv);
;                         else {
;                             const f32x4 r = cg[m] * cv;
;                             v2u w; w.x = cvt_pk_bf16(r[0], r[1]); w.y = cvt_pk_bf16(r[2], r[3]);
;                             *(v2u*)(ACT + (size_t)(rowb + 16 * m + fr) * FF + 128 * u.pn + 32 * wc + 8 * fq + 4 * n) = w;
;                         }
	v_pk_fma_f32 v[254:255], v[206:207], v[80:81], v[254:255]
	v_pk_fma_f32 v[148:149], v[208:209], v[82:83], v[148:149]
	v_and_b32_e32 v246, 0x7fffffff, v254
	v_and_b32_e32 v247, 0x7fffffff, v255
	v_and_b32_e32 v250, 0x7fffffff, v148
	v_and_b32_e32 v251, 0x7fffffff, v149
	v_pk_fma_f32 v[246:247], v[246:247], s[38:39], 1.0 op_sel_hi:[1,0,0]
	v_pk_fma_f32 v[250:251], v[250:251], s[38:39], 1.0 op_sel_hi:[1,0,0]
	v_pk_mul_f32 v[248:249], v[254:255], v[254:255]
	v_pk_mul_f32 v[252:253], v[148:149], v[148:149]
	v_rcp_f32_e32 v246, v246
	v_rcp_f32_e32 v247, v247
	v_rcp_f32_e32 v250, v250
	v_rcp_f32_e32 v251, v251
	v_pk_mul_f32 v[248:249], v[248:249], s[72:73] op_sel_hi:[1,0]
	v_pk_mul_f32 v[252:253], v[252:253], s[72:73] op_sel_hi:[1,0]
	v_mov_b64_e32 v[238:239], s[64:65]
	v_mov_b64_e32 v[240:241], s[64:65]
	v_exp_f32_e32 v248, v248
	v_exp_f32_e32 v249, v249
	v_exp_f32_e32 v252, v252
	v_exp_f32_e32 v253, v253
	v_pk_fma_f32 v[238:239], v[246:247], s[62:63], v[238:239] op_sel_hi:[1,0,0]
	v_pk_fma_f32 v[240:241], v[250:251], s[62:63], v[240:241] op_sel_hi:[1,0,0]
	v_pk_fma_f32 v[238:239], v[246:247], v[238:239], s[66:67] op_sel_hi:[1,1,0]
	v_pk_fma_f32 v[240:241], v[250:251], v[240:241], s[66:67] op_sel_hi:[1,1,0]
	v_pk_fma_f32 v[238:239], v[246:247], v[238:239], s[68:69] op_sel_hi:[1,1,0]
	v_pk_fma_f32 v[240:241], v[250:251], v[240:241], s[68:69] op_sel_hi:[1,1,0]
	v_pk_fma_f32 v[238:239], v[246:247], v[238:239], s[70:71] op_sel_hi:[1,1,0]
	v_pk_fma_f32 v[240:241], v[250:251], v[240:241], s[70:71] op_sel_hi:[1,1,0]
	v_pk_mul_f32 v[238:239], v[246:247], v[238:239]
	v_pk_mul_f32 v[240:241], v[250:251], v[240:241]
	v_pk_mul_f32 v[238:239], v[248:249], v[238:239]
	v_pk_mul_f32 v[240:241], v[252:253], v[240:241]
	v_cmp_gt_f32_e64 vcc, 0, v254
	v_cmp_gt_f32_e64 s[56:57], 0, v148
	v_cmp_gt_f32_e64 s[14:15], 0, v255
	v_cmp_gt_f32_e64 s[92:93], 0, v149
	v_pk_mul_f32 v[248:249], v[254:255], v[238:239]
	v_pk_mul_f32 v[252:253], v[148:149], v[240:241]
	v_pk_fma_f32 v[238:239], v[254:255], v[238:239], v[254:255] neg_lo:[1,0,0] neg_hi:[1,0,0]
	v_pk_fma_f32 v[240:241], v[148:149], v[240:241], v[148:149] neg_lo:[1,0,0] neg_hi:[1,0,0]
	v_cndmask_b32_e64 v238, v238, v248, vcc
	v_cndmask_b32_e64 v240, v240, v252, s[56:57]
	v_cndmask_b32_e64 v239, v239, v249, s[14:15]
	v_cndmask_b32_e64 v241, v241, v253, s[92:93]
	v_mov_b32_dpp v246, v68 row_ror:1 row_mask:0xf bank_mask:0xf
	v_mov_b32_dpp v250, v68 row_ror:2 row_mask:0xf bank_mask:0xf
	v_mov_b32_dpp v247, v69 row_ror:1 row_mask:0xf bank_mask:0xf
	v_mov_b32_dpp v251, v69 row_ror:2 row_mask:0xf bank_mask:0xf
	v_mov_b32_dpp v248, v70 row_ror:1 row_mask:0xf bank_mask:0xf
	v_mov_b32_dpp v252, v70 row_ror:2 row_mask:0xf bank_mask:0xf
	v_mov_b32_dpp v249, v71 row_ror:1 row_mask:0xf bank_mask:0xf
	v_mov_b32_dpp v253, v71 row_ror:2 row_mask:0xf bank_mask:0xf
	v_mov_b32_dpp v246, v64 row_shr:1 row_mask:0xf bank_mask:0xf
	v_mov_b32_dpp v250, v64 row_shr:2 row_mask:0xf bank_mask:0xf
	v_mov_b32_dpp v247, v65 row_shr:1 row_mask:0xf bank_mask:0xf
	v_mov_b32_dpp v251, v65 row_shr:2 row_mask:0xf bank_mask:0xf
	v_mov_b32_dpp v248, v66 row_shr:1 row_mask:0xf bank_mask:0xf
	v_mov_b32_dpp v252, v66 row_shr:2 row_mask:0xf bank_mask:0xf
	v_mov_b32_dpp v249, v67 row_shr:1 row_mask:0xf bank_mask:0xf
	v_mov_b32_dpp v253, v67 row_shr:2 row_mask:0xf bank_mask:0xf
	v_pk_fma_f32 v[254:255], v[182:183], v[250:251], v[144:145]
	v_pk_fma_f32 v[148:149], v[184:185], v[252:253], v[146:147]
	v_pk_fma_f32 v[254:255], v[198:199], v[246:247], v[254:255]
	v_pk_fma_f32 v[148:149], v[200:201], v[248:249], v[148:149]
	v_pk_fma_f32 v[254:255], v[128:129], v[64:65], v[254:255]
	v_pk_fma_f32 v[148:149], v[130:131], v[66:67], v[148:149]
	v_pk_mul_f32 v[254:255], v[238:239], v[254:255]
	v_pk_mul_f32 v[148:149], v[240:241], v[148:149]
	v_cvt_pk_bf16_f32 v244, v254, v255
	v_cvt_pk_bf16_f32 v245, v148, v149
	s_add_u32 s56, s46, 0x42000
	s_addc_u32 s57, s47, 0
	global_store_dwordx4 v151, v[242:245], s[56:57]
	s_waitcnt vmcnt(3)
	v_mov_b32_dpp v246, v220 row_ror:1 row_mask:0xf bank_mask:0xf
	v_mov_b32_dpp v250, v220 row_ror:2 row_mask:0xf bank_mask:0xf
	v_mov_b32_dpp v247, v221 row_ror:1 row_mask:0xf bank_mask:0xf
	v_mov_b32_dpp v251, v221 row_ror:2 row_mask:0xf bank_mask:0xf
	v_mov_b32_dpp v248, v222 row_ror:1 row_mask:0xf bank_mask:0xf
	v_mov_b32_dpp v252, v222 row_ror:2 row_mask:0xf bank_mask:0xf
	v_mov_b32_dpp v249, v223 row_ror:1 row_mask:0xf bank_mask:0xf
	v_mov_b32_dpp v253, v223 row_ror:2 row_mask:0xf bank_mask:0xf
	v_mov_b32_dpp v246, v60 row_shr:1 row_mask:0xf bank_mask:0xf
	v_mov_b32_dpp v250, v60 row_shr:2 row_mask:0xf bank_mask:0xf
	v_mov_b32_dpp v247, v61 row_shr:1 row_mask:0xf bank_mask:0xf
	v_mov_b32_dpp v251, v61 row_shr:2 row_mask:0xf bank_mask:0xf
	v_mov_b32_dpp v248, v62 row_shr:1 row_mask:0xf bank_mask:0xf
	v_mov_b32_dpp v252, v62 row_shr:2 row_mask:0xf bank_mask:0xf
	v_mov_b32_dpp v249, v63 row_shr:1 row_mask:0xf bank_mask:0xf
	v_mov_b32_dpp v253, v63 row_shr:2 row_mask:0xf bank_mask:0xf
	v_pk_fma_f32 v[254:255], v[170:171], v[250:251], v[132:133]
	v_pk_fma_f32 v[148:149], v[172:173], v[252:253], v[134:135]
	v_pk_fma_f32 v[254:255], v[186:187], v[246:247], v[254:255]
	v_pk_fma_f32 v[148:149], v[188:189], v[248:249], v[148:149]
	v_pk_fma_f32 v[254:255], v[202:203], v[60:61], v[254:255]
	v_pk_fma_f32 v[148:149], v[204:205], v[62:63], v[148:149]
	v_and_b32_e32 v246, 0x7fffffff, v254
	v_and_b32_e32 v247, 0x7fffffff, v255
	v_and_b32_e32 v250, 0x7fffffff, v148
	v_and_b32_e32 v251, 0x7fffffff, v149
	v_pk_fma_f32 v[246:247], v[246:247], s[38:39], 1.0 op_sel_hi:[1,0,0]
	v_pk_fma_f32 v[250:251], v[250:251], s[38:39], 1.0 op_sel_hi:[1,0,0]
;     __device__ __forceinline__ void operator()(const f32x4 (&acc)[2][2][4][2], const Unit& u, int wr, int wc, int fr, int fq) const {
;     ...
;                         if ((blk & 31) != 0 && fr >= 14) hv = *(const f32x4*)(HALO + (size_t)(2 * blk + fr - 14) * FF2 + cgc);
;                         if ((u.pm & 7) == 7 && ai == 1 && wr == 1 && fr >= 14) *(f32x4*)(ncp + (size_t)((u.pm >> 3) * 2 + (fr - 14)) * FF2 + oc) = v[3];
;                     }
; #pragma unroll
;                     for (int m = 0; m < 4; ++m) {
;                         f32x4 cv;
;                         if (!samp) {
;                             const f32x4 prev = m ? v[m - 1] : hv;
; #pragma unroll
;                             for (int e = 0; e < 4; ++e) {
;                                 const int vi = __float_as_int(v[m][e]), pi = __float_as_int(prev[e]);
;                                 const int o1 = __builtin_amdgcn_mov_dpp(pi, 0x121, 0xf, 0xf, false);
;                                 const int o2 = __builtin_amdgcn_mov_dpp(pi, 0x122, 0xf, 0xf, false);
;                                 const float p1 = __int_as_float(__builtin_amdgcn_update_dpp(o1, vi, 0x111, 0xf, 0xf, false));
;                                 const float p2 = __int_as_float(__builtin_amdgcn_update_dpp(o2, vi, 0x112, 0xf, 0xf, false));
;                                 cv[e] = cb[e] + cw0[e] * p2 + cw1[e] * p1 + cw2[e] * v[m][e];
;                             }
;                         } else {
;                             const int ns = rowb + 16 * m + fr - MP;
;                             f32x4 s0 = (f32x4){0.f, 0.f, 0.f, 0.f}, s1 = s0;
;                             if (ns < NS) {
;                                 s0 = *(const f32x4*)(state + (size_t)(ns * 2 + 0) * FF2 + oc); s1 = *(const f32x4*)(state + (size_t)(ns * 2 + 1) * FF2 + oc);
;                                 *(f32x4*)(ncs + (size_t)(ns * 2 + 0) * FF2 + oc) = s1; *(f32x4*)(ncs + (size_t)(ns * 2 + 1) * FF2 + oc) = v[m];
;                             }
;                             cv = cb + cw0 * s0 + cw1 * s1 + cw2 * v[m];
;                         }
;                         if (bj == 0) cg[m] = gelu4(cv);
;                         else {
;                             const f32x4 r = cg[m] * cv;
;                             v2u w; w.x = cvt_pk_bf16(r[0], r[1]); w.y = cvt_pk_bf16(r[2], r[3]);
	v_pk_mul_f32 v[248:249], v[254:255], v[254:255]
	v_pk_mul_f32 v[252:253], v[148:149], v[148:149]
	v_rcp_f32_e32 v246, v246
	v_rcp_f32_e32 v247, v247
	v_rcp_f32_e32 v250, v250
	v_rcp_f32_e32 v251, v251
	v_pk_mul_f32 v[248:249], v[248:249], s[72:73] op_sel_hi:[1,0]
	v_pk_mul_f32 v[252:253], v[252:253], s[72:73] op_sel_hi:[1,0]
	v_mov_b64_e32 v[238:239], s[64:65]
	v_mov_b64_e32 v[240:241], s[64:65]
	v_exp_f32_e32 v248, v248
	v_exp_f32_e32 v249, v249
	v_exp_f32_e32 v252, v252
	v_exp_f32_e32 v253, v253
	v_pk_fma_f32 v[238:239], v[246:247], s[62:63], v[238:239] op_sel_hi:[1,0,0]
	v_pk_fma_f32 v[240:241], v[250:251], s[62:63], v[240:241] op_sel_hi:[1,0,0]
	v_pk_fma_f32 v[238:239], v[246:247], v[238:239], s[66:67] op_sel_hi:[1,1,0]
	v_pk_fma_f32 v[240:241], v[250:251], v[240:241], s[66:67] op_sel_hi:[1,1,0]
	v_pk_fma_f32 v[238:239], v[246:247], v[238:239], s[68:69] op_sel_hi:[1,1,0]
	v_pk_fma_f32 v[240:241], v[250:251], v[240:241], s[68:69] op_sel_hi:[1,1,0]
	v_pk_fma_f32 v[238:239], v[246:247], v[238:239], s[70:71] op_sel_hi:[1,1,0]
	v_pk_fma_f32 v[240:241], v[250:251], v[240:241], s[70:71] op_sel_hi:[1,1,0]
	v_pk_mul_f32 v[238:239], v[246:247], v[238:239]
	v_pk_mul_f32 v[240:241], v[250:251], v[240:241]
	v_pk_mul_f32 v[238:239], v[248:249], v[238:239]
	v_pk_mul_f32 v[240:241], v[252:253], v[240:241]
	v_cmp_gt_f32_e64 vcc, 0, v254
	v_cmp_gt_f32_e64 s[56:57], 0, v148
	v_cmp_gt_f32_e64 s[14:15], 0, v255
	v_cmp_gt_f32_e64 s[92:93], 0, v149
	v_pk_mul_f32 v[248:249], v[254:255], v[238:239]
	v_pk_mul_f32 v[252:253], v[148:149], v[240:241]
	v_pk_fma_f32 v[238:239], v[254:255], v[238:239], v[254:255] neg_lo:[1,0,0] neg_hi:[1,0,0]
	v_pk_fma_f32 v[240:241], v[148:149], v[240:241], v[148:149] neg_lo:[1,0,0] neg_hi:[1,0,0]
	v_cndmask_b32_e64 v238, v238, v248, vcc
	v_cndmask_b32_e64 v240, v240, v252, s[56:57]
	v_cndmask_b32_e64 v239, v239, v249, s[14:15]
	v_cndmask_b32_e64 v241, v241, v253, s[92:93]
	v_mov_b32_dpp v246, v228 row_ror:1 row_mask:0xf bank_mask:0xf
	v_mov_b32_dpp v250, v228 row_ror:2 row_mask:0xf bank_mask:0xf
	v_mov_b32_dpp v247, v229 row_ror:1 row_mask:0xf bank_mask:0xf
	v_mov_b32_dpp v251, v229 row_ror:2 row_mask:0xf bank_mask:0xf
	v_mov_b32_dpp v248, v230 row_ror:1 row_mask:0xf bank_mask:0xf
	v_mov_b32_dpp v252, v230 row_ror:2 row_mask:0xf bank_mask:0xf
	v_mov_b32_dpp v249, v231 row_ror:1 row_mask:0xf bank_mask:0xf
	v_mov_b32_dpp v253, v231 row_ror:2 row_mask:0xf bank_mask:0xf
	v_mov_b32_dpp v246, v44 row_shr:1 row_mask:0xf bank_mask:0xf
	v_mov_b32_dpp v250, v44 row_shr:2 row_mask:0xf bank_mask:0xf
	v_mov_b32_dpp v247, v45 row_shr:1 row_mask:0xf bank_mask:0xf
	v_mov_b32_dpp v251, v45 row_shr:2 row_mask:0xf bank_mask:0xf
	v_mov_b32_dpp v248, v46 row_shr:1 row_mask:0xf bank_mask:0xf
	v_mov_b32_dpp v252, v46 row_shr:2 row_mask:0xf bank_mask:0xf
	v_mov_b32_dpp v249, v47 row_shr:1 row_mask:0xf bank_mask:0xf
	v_mov_b32_dpp v253, v47 row_shr:2 row_mask:0xf bank_mask:0xf
	v_pk_fma_f32 v[254:255], v[178:179], v[250:251], v[140:141]
	v_pk_fma_f32 v[148:149], v[180:181], v[252:253], v[142:143]
	v_pk_fma_f32 v[254:255], v[194:195], v[246:247], v[254:255]
	v_pk_fma_f32 v[148:149], v[196:197], v[248:249], v[148:149]
	v_pk_fma_f32 v[254:255], v[210:211], v[44:45], v[254:255]
	v_pk_fma_f32 v[148:149], v[212:213], v[46:47], v[148:149]
	v_pk_mul_f32 v[254:255], v[238:239], v[254:255]
	v_pk_mul_f32 v[148:149], v[240:241], v[148:149]
	v_cvt_pk_bf16_f32 v242, v254, v255
	v_cvt_pk_bf16_f32 v243, v148, v149
	v_mov_b32_dpp v246, v224 row_ror:1 row_mask:0xf bank_mask:0xf
	v_mov_b32_dpp v250, v224 row_ror:2 row_mask:0xf bank_mask:0xf
	v_mov_b32_dpp v247, v225 row_ror:1 row_mask:0xf bank_mask:0xf
	v_mov_b32_dpp v251, v225 row_ror:2 row_mask:0xf bank_mask:0xf
	v_mov_b32_dpp v248, v226 row_ror:1 row_mask:0xf bank_mask:0xf
	v_mov_b32_dpp v252, v226 row_ror:2 row_mask:0xf bank_mask:0xf
	v_mov_b32_dpp v249, v227 row_ror:1 row_mask:0xf bank_mask:0xf
	v_mov_b32_dpp v253, v227 row_ror:2 row_mask:0xf bank_mask:0xf
	v_mov_b32_dpp v246, v28 row_shr:1 row_mask:0xf bank_mask:0xf
	v_mov_b32_dpp v250, v28 row_shr:2 row_mask:0xf bank_mask:0xf
	v_mov_b32_dpp v247, v29 row_shr:1 row_mask:0xf bank_mask:0xf
	v_mov_b32_dpp v251, v29 row_shr:2 row_mask:0xf bank_mask:0xf
	v_mov_b32_dpp v248, v30 row_shr:1 row_mask:0xf bank_mask:0xf
	v_mov_b32_dpp v252, v30 row_shr:2 row_mask:0xf bank_mask:0xf
	v_mov_b32_dpp v249, v31 row_shr:1 row_mask:0xf bank_mask:0xf
	v_mov_b32_dpp v253, v31 row_shr:2 row_mask:0xf bank_mask:0xf
	v_pk_fma_f32 v[254:255], v[174:175], v[250:251], v[136:137]
	v_pk_fma_f32 v[148:149], v[176:177], v[252:253], v[138:139]
	v_pk_fma_f32 v[254:255], v[190:191], v[246:247], v[254:255]
	v_pk_fma_f32 v[148:149], v[192:193], v[248:249], v[148:149]
	v_pk_fma_f32 v[254:255], v[206:207], v[28:29], v[254:255]
	v_pk_fma_f32 v[148:149], v[208:209], v[30:31], v[148:149]
	v_and_b32_e32 v246, 0x7fffffff, v254
	v_and_b32_e32 v247, 0x7fffffff, v255
	v_and_b32_e32 v250, 0x7fffffff, v148
	v_and_b32_e32 v251, 0x7fffffff, v149
	v_pk_fma_f32 v[246:247], v[246:247], s[38:39], 1.0 op_sel_hi:[1,0,0]
	v_pk_fma_f32 v[250:251], v[250:251], s[38:39], 1.0 op_sel_hi:[1,0,0]
	v_pk_mul_f32 v[248:249], v[254:255], v[254:255]
	v_pk_mul_f32 v[252:253], v[148:149], v[148:149]
	v_rcp_f32_e32 v246, v246
	v_rcp_f32_e32 v247, v247
	v_rcp_f32_e32 v250, v250
	v_rcp_f32_e32 v251, v251
	v_pk_mul_f32 v[248:249], v[248:249], s[72:73] op_sel_hi:[1,0]
	v_pk_mul_f32 v[252:253], v[252:253], s[72:73] op_sel_hi:[1,0]
	v_mov_b64_e32 v[238:239], s[64:65]
	v_mov_b64_e32 v[240:241], s[64:65]
	v_exp_f32_e32 v248, v248
	v_exp_f32_e32 v249, v249
	v_exp_f32_e32 v252, v252
	v_exp_f32_e32 v253, v253
; __device__ __forceinline__ f32x2 gelu_pk(f32x2 v) {
;     const f32x2 av = __builtin_elementwise_abs(v), d = av * 0.2316418882f + 1.0f;
;     __device__ __forceinline__ void operator()(const f32x4 (&acc)[2][2][4][2], const Unit& u, int wr, int wc, int fr, int fq) const {
;     ...
; #pragma unroll
;                     for (int m = 0; m < 4; ++m) {
;                         f32x4 cv;
;                         if (!samp) {
;                             const f32x4 prev = m ? v[m - 1] : hv;
; #pragma unroll
;                             for (int e = 0; e < 4; ++e) {
;                                 const int vi = __float_as_int(v[m][e]), pi = __float_as_int(prev[e]);
;                                 const int o1 = __builtin_amdgcn_mov_dpp(pi, 0x121, 0xf, 0xf, false);
;                                 const int o2 = __builtin_amdgcn_mov_dpp(pi, 0x122, 0xf, 0xf, false);
;                                 const float p1 = __int_as_float(__builtin_amdgcn_update_dpp(o1, vi, 0x111, 0xf, 0xf, false));
;                                 const float p2 = __int_as_float(__builtin_amdgcn_update_dpp(o2, vi, 0x112, 0xf, 0xf, false));
;                                 cv[e] = cb[e] + cw0[e] * p2 + cw1[e] * p1 + cw2[e] * v[m][e];
;                             }
;                         } else {
;                             const int ns = rowb + 16 * m + fr - MP;
;                             f32x4 s0 = (f32x4){0.f, 0.f, 0.f, 0.f}, s1 = s0;
;                             if (ns < NS) {
;                                 s0 = *(const f32x4*)(state + (size_t)(ns * 2 + 0) * FF2 + oc); s1 = *(const f32x4*)(state + (size_t)(ns * 2 + 1) * FF2 + oc);
;                                 *(f32x4*)(ncs + (size_t)(ns * 2 + 0) * FF2 + oc) = s1; *(f32x4*)(ncs + (size_t)(ns * 2 + 1) * FF2 + oc) = v[m];
;                             }
;                             cv = cb + cw0 * s0 + cw1 * s1 + cw2 * v[m];
;                         }
;                         if (bj == 0) cg[m] = gelu4(cv);
;                         else {
;                             const f32x4 r = cg[m] * cv;
;                             v2u w; w.x = cvt_pk_bf16(r[0], r[1]); w.y = cvt_pk_bf16(r[2], r[3]);
;                             *(v2u*)(ACT + (size_t)(rowb + 16 * m + fr) * FF + 128 * u.pn + 32 * wc + 8 * fq + 4 * n) = w;
;                         }
	v_pk_fma_f32 v[238:239], v[246:247], s[62:63], v[238:239] op_sel_hi:[1,0,0]
	v_pk_fma_f32 v[240:241], v[250:251], s[62:63], v[240:241] op_sel_hi:[1,0,0]
	v_pk_fma_f32 v[238:239], v[246:247], v[238:239], s[66:67] op_sel_hi:[1,1,0]
	v_pk_fma_f32 v[240:241], v[250:251], v[240:241], s[66:67] op_sel_hi:[1,1,0]
	v_pk_fma_f32 v[238:239], v[246:247], v[238:239], s[68:69] op_sel_hi:[1,1,0]
	v_pk_fma_f32 v[240:241], v[250:251], v[240:241], s[68:69] op_sel_hi:[1,1,0]
	v_pk_fma_f32 v[238:239], v[246:247], v[238:239], s[70:71] op_sel_hi:[1,1,0]
	v_pk_fma_f32 v[240:241], v[250:251], v[240:241], s[70:71] op_sel_hi:[1,1,0]
	v_pk_mul_f32 v[238:239], v[246:247], v[238:239]
	v_pk_mul_f32 v[240:241], v[250:251], v[240:241]
	v_pk_mul_f32 v[238:239], v[248:249], v[238:239]
	v_pk_mul_f32 v[240:241], v[252:253], v[240:241]
	v_cmp_gt_f32_e64 vcc, 0, v254
	v_cmp_gt_f32_e64 s[56:57], 0, v148
	v_cmp_gt_f32_e64 s[14:15], 0, v255
	v_cmp_gt_f32_e64 s[92:93], 0, v149
	v_pk_mul_f32 v[248:249], v[254:255], v[238:239]
	v_pk_mul_f32 v[252:253], v[148:149], v[240:241]
	v_pk_fma_f32 v[238:239], v[254:255], v[238:239], v[254:255] neg_lo:[1,0,0] neg_hi:[1,0,0]
	v_pk_fma_f32 v[240:241], v[148:149], v[240:241], v[148:149] neg_lo:[1,0,0] neg_hi:[1,0,0]
	v_cndmask_b32_e64 v238, v238, v248, vcc
	v_cndmask_b32_e64 v240, v240, v252, s[56:57]
	v_cndmask_b32_e64 v239, v239, v249, s[14:15]
	v_cndmask_b32_e64 v241, v241, v253, s[92:93]
	v_mov_b32_dpp v246, v232 row_ror:1 row_mask:0xf bank_mask:0xf
	v_mov_b32_dpp v250, v232 row_ror:2 row_mask:0xf bank_mask:0xf
	v_mov_b32_dpp v247, v233 row_ror:1 row_mask:0xf bank_mask:0xf
	v_mov_b32_dpp v251, v233 row_ror:2 row_mask:0xf bank_mask:0xf
	v_mov_b32_dpp v248, v234 row_ror:1 row_mask:0xf bank_mask:0xf
	v_mov_b32_dpp v252, v234 row_ror:2 row_mask:0xf bank_mask:0xf
	v_mov_b32_dpp v249, v235 row_ror:1 row_mask:0xf bank_mask:0xf
	v_mov_b32_dpp v253, v235 row_ror:2 row_mask:0xf bank_mask:0xf
	v_mov_b32_dpp v246, v12 row_shr:1 row_mask:0xf bank_mask:0xf
	v_mov_b32_dpp v250, v12 row_shr:2 row_mask:0xf bank_mask:0xf
	v_mov_b32_dpp v247, v13 row_shr:1 row_mask:0xf bank_mask:0xf
	v_mov_b32_dpp v251, v13 row_shr:2 row_mask:0xf bank_mask:0xf
	v_mov_b32_dpp v248, v14 row_shr:1 row_mask:0xf bank_mask:0xf
	v_mov_b32_dpp v252, v14 row_shr:2 row_mask:0xf bank_mask:0xf
	v_mov_b32_dpp v249, v15 row_shr:1 row_mask:0xf bank_mask:0xf
	v_mov_b32_dpp v253, v15 row_shr:2 row_mask:0xf bank_mask:0xf
	v_pk_fma_f32 v[254:255], v[182:183], v[250:251], v[144:145]
	v_pk_fma_f32 v[148:149], v[184:185], v[252:253], v[146:147]
	v_pk_fma_f32 v[254:255], v[198:199], v[246:247], v[254:255]
	v_pk_fma_f32 v[148:149], v[200:201], v[248:249], v[148:149]
	v_pk_fma_f32 v[254:255], v[128:129], v[12:13], v[254:255]
	v_pk_fma_f32 v[148:149], v[130:131], v[14:15], v[148:149]
	v_pk_mul_f32 v[254:255], v[238:239], v[254:255]
	v_pk_mul_f32 v[148:149], v[240:241], v[148:149]
	v_cvt_pk_bf16_f32 v244, v254, v255
	v_cvt_pk_bf16_f32 v245, v148, v149
	s_add_u32 s56, s46, 0xb0000
	s_addc_u32 s57, s47, 0
	global_store_dwordx4 v151, v[242:245], s[56:57]
	v_mov_b32_dpp v246, v60 row_ror:1 row_mask:0xf bank_mask:0xf
	v_mov_b32_dpp v250, v60 row_ror:2 row_mask:0xf bank_mask:0xf
	v_mov_b32_dpp v247, v61 row_ror:1 row_mask:0xf bank_mask:0xf
	v_mov_b32_dpp v251, v61 row_ror:2 row_mask:0xf bank_mask:0xf
	v_mov_b32_dpp v248, v62 row_ror:1 row_mask:0xf bank_mask:0xf
	v_mov_b32_dpp v252, v62 row_ror:2 row_mask:0xf bank_mask:0xf
	v_mov_b32_dpp v249, v63 row_ror:1 row_mask:0xf bank_mask:0xf
	v_mov_b32_dpp v253, v63 row_ror:2 row_mask:0xf bank_mask:0xf
	v_mov_b32_dpp v246, v52 row_shr:1 row_mask:0xf bank_mask:0xf
	v_mov_b32_dpp v250, v52 row_shr:2 row_mask:0xf bank_mask:0xf
	v_mov_b32_dpp v247, v53 row_shr:1 row_mask:0xf bank_mask:0xf
	v_mov_b32_dpp v251, v53 row_shr:2 row_mask:0xf bank_mask:0xf
	v_mov_b32_dpp v248, v54 row_shr:1 row_mask:0xf bank_mask:0xf
	v_mov_b32_dpp v252, v54 row_shr:2 row_mask:0xf bank_mask:0xf
	v_mov_b32_dpp v249, v55 row_shr:1 row_mask:0xf bank_mask:0xf
	v_mov_b32_dpp v253, v55 row_shr:2 row_mask:0xf bank_mask:0xf
	v_pk_fma_f32 v[254:255], v[170:171], v[250:251], v[132:133]
	v_pk_fma_f32 v[148:149], v[172:173], v[252:253], v[134:135]
	v_pk_fma_f32 v[254:255], v[186:187], v[246:247], v[254:255]
	v_pk_fma_f32 v[148:149], v[188:189], v[248:249], v[148:149]
	v_pk_fma_f32 v[254:255], v[202:203], v[52:53], v[254:255]
	v_pk_fma_f32 v[148:149], v[204:205], v[54:55], v[148:149]
	v_and_b32_e32 v246, 0x7fffffff, v254
	v_and_b32_e32 v247, 0x7fffffff, v255
	v_and_b32_e32 v250, 0x7fffffff, v148
	v_and_b32_e32 v251, 0x7fffffff, v149
	v_pk_fma_f32 v[246:247], v[246:247], s[38:39], 1.0 op_sel_hi:[1,0,0]
	v_pk_fma_f32 v[250:251], v[250:251], s[38:39], 1.0 op_sel_hi:[1,0,0]
	v_pk_mul_f32 v[248:249], v[254:255], v[254:255]
	v_pk_mul_f32 v[252:253], v[148:149], v[148:149]
	v_rcp_f32_e32 v246, v246
	v_rcp_f32_e32 v247, v247
	v_rcp_f32_e32 v250, v250
	v_rcp_f32_e32 v251, v251
	v_pk_mul_f32 v[248:249], v[248:249], s[72:73] op_sel_hi:[1,0]
	v_pk_mul_f32 v[252:253], v[252:253], s[72:73] op_sel_hi:[1,0]
	v_mov_b64_e32 v[238:239], s[64:65]
	v_mov_b64_e32 v[240:241], s[64:65]
	v_exp_f32_e32 v248, v248
	v_exp_f32_e32 v249, v249
	v_exp_f32_e32 v252, v252
	v_exp_f32_e32 v253, v253
	v_pk_fma_f32 v[238:239], v[246:247], s[62:63], v[238:239] op_sel_hi:[1,0,0]
	v_pk_fma_f32 v[240:241], v[250:251], s[62:63], v[240:241] op_sel_hi:[1,0,0]
	v_pk_fma_f32 v[238:239], v[246:247], v[238:239], s[66:67] op_sel_hi:[1,1,0]
	v_pk_fma_f32 v[240:241], v[250:251], v[240:241], s[66:67] op_sel_hi:[1,1,0]
	v_pk_fma_f32 v[238:239], v[246:247], v[238:239], s[68:69] op_sel_hi:[1,1,0]
	v_pk_fma_f32 v[240:241], v[250:251], v[240:241], s[68:69] op_sel_hi:[1,1,0]
; __device__ __forceinline__ f32x2 gelu_pk(f32x2 v) {
;     const f32x2 av = __builtin_elementwise_abs(v), d = av * 0.2316418882f + 1.0f;
;     __device__ __forceinline__ void operator()(const f32x4 (&acc)[2][2][4][2], const Unit& u, int wr, int wc, int fr, int fq) const {
;     ...
; #pragma unroll
;                     for (int m = 0; m < 4; ++m) {
;                         f32x4 cv;
;                         if (!samp) {
;                             const f32x4 prev = m ? v[m - 1] : hv;
; #pragma unroll
;                             for (int e = 0; e < 4; ++e) {
;                                 const int vi = __float_as_int(v[m][e]), pi = __float_as_int(prev[e]);
;                                 const int o1 = __builtin_amdgcn_mov_dpp(pi, 0x121, 0xf, 0xf, false);
;                                 const int o2 = __builtin_amdgcn_mov_dpp(pi, 0x122, 0xf, 0xf, false);
;                                 const float p1 = __int_as_float(__builtin_amdgcn_update_dpp(o1, vi, 0x111, 0xf, 0xf, false));
;                                 const float p2 = __int_as_float(__builtin_amdgcn_update_dpp(o2, vi, 0x112, 0xf, 0xf, false));
;                                 cv[e] = cb[e] + cw0[e] * p2 + cw1[e] * p1 + cw2[e] * v[m][e];
;                             }
;                         } else {
;                             const int ns = rowb + 16 * m + fr - MP;
;                             f32x4 s0 = (f32x4){0.f, 0.f, 0.f, 0.f}, s1 = s0;
;                             if (ns < NS) {
;                                 s0 = *(const f32x4*)(state + (size_t)(ns * 2 + 0) * FF2 + oc); s1 = *(const f32x4*)(state + (size_t)(ns * 2 + 1) * FF2 + oc);
;                                 *(f32x4*)(ncs + (size_t)(ns * 2 + 0) * FF2 + oc) = s1; *(f32x4*)(ncs + (size_t)(ns * 2 + 1) * FF2 + oc) = v[m];
;                             }
;                             cv = cb + cw0 * s0 + cw1 * s1 + cw2 * v[m];
;                         }
;                         if (bj == 0) cg[m] = gelu4(cv);
;                         else {
;                             const f32x4 r = cg[m] * cv;
;                             v2u w; w.x = cvt_pk_bf16(r[0], r[1]); w.y = cvt_pk_bf16(r[2], r[3]);
;                             *(v2u*)(ACT + (size_t)(rowb + 16 * m + fr) * FF + 128 * u.pn + 32 * wc + 8 * fq + 4 * n) = w;
;                         }
	v_pk_fma_f32 v[238:239], v[246:247], v[238:239], s[70:71] op_sel_hi:[1,1,0]
	v_pk_fma_f32 v[240:241], v[250:251], v[240:241], s[70:71] op_sel_hi:[1,1,0]
	v_pk_mul_f32 v[238:239], v[246:247], v[238:239]
	v_pk_mul_f32 v[240:241], v[250:251], v[240:241]
	v_pk_mul_f32 v[238:239], v[248:249], v[238:239]
	v_pk_mul_f32 v[240:241], v[252:253], v[240:241]
	v_cmp_gt_f32_e64 vcc, 0, v254
	v_cmp_gt_f32_e64 s[56:57], 0, v148
	v_cmp_gt_f32_e64 s[14:15], 0, v255
	v_cmp_gt_f32_e64 s[92:93], 0, v149
	v_pk_mul_f32 v[248:249], v[254:255], v[238:239]
	v_pk_mul_f32 v[252:253], v[148:149], v[240:241]
	v_pk_fma_f32 v[238:239], v[254:255], v[238:239], v[254:255] neg_lo:[1,0,0] neg_hi:[1,0,0]
	v_pk_fma_f32 v[240:241], v[148:149], v[240:241], v[148:149] neg_lo:[1,0,0] neg_hi:[1,0,0]
	v_cndmask_b32_e64 v238, v238, v248, vcc
	v_cndmask_b32_e64 v240, v240, v252, s[56:57]
	v_cndmask_b32_e64 v239, v239, v249, s[14:15]
	v_cndmask_b32_e64 v241, v241, v253, s[92:93]
	v_mov_b32_dpp v246, v44 row_ror:1 row_mask:0xf bank_mask:0xf
	v_mov_b32_dpp v250, v44 row_ror:2 row_mask:0xf bank_mask:0xf
	v_mov_b32_dpp v247, v45 row_ror:1 row_mask:0xf bank_mask:0xf
	v_mov_b32_dpp v251, v45 row_ror:2 row_mask:0xf bank_mask:0xf
	v_mov_b32_dpp v248, v46 row_ror:1 row_mask:0xf bank_mask:0xf
	v_mov_b32_dpp v252, v46 row_ror:2 row_mask:0xf bank_mask:0xf
	v_mov_b32_dpp v249, v47 row_ror:1 row_mask:0xf bank_mask:0xf
	v_mov_b32_dpp v253, v47 row_ror:2 row_mask:0xf bank_mask:0xf
	v_mov_b32_dpp v246, v36 row_shr:1 row_mask:0xf bank_mask:0xf
	v_mov_b32_dpp v250, v36 row_shr:2 row_mask:0xf bank_mask:0xf
	v_mov_b32_dpp v247, v37 row_shr:1 row_mask:0xf bank_mask:0xf
	v_mov_b32_dpp v251, v37 row_shr:2 row_mask:0xf bank_mask:0xf
	v_mov_b32_dpp v248, v38 row_shr:1 row_mask:0xf bank_mask:0xf
	v_mov_b32_dpp v252, v38 row_shr:2 row_mask:0xf bank_mask:0xf
	v_mov_b32_dpp v249, v39 row_shr:1 row_mask:0xf bank_mask:0xf
	v_mov_b32_dpp v253, v39 row_shr:2 row_mask:0xf bank_mask:0xf
	v_pk_fma_f32 v[254:255], v[178:179], v[250:251], v[140:141]
	v_pk_fma_f32 v[148:149], v[180:181], v[252:253], v[142:143]
	v_pk_fma_f32 v[254:255], v[194:195], v[246:247], v[254:255]
	v_pk_fma_f32 v[148:149], v[196:197], v[248:249], v[148:149]
	v_pk_fma_f32 v[254:255], v[210:211], v[36:37], v[254:255]
	v_pk_fma_f32 v[148:149], v[212:213], v[38:39], v[148:149]
	v_pk_mul_f32 v[254:255], v[238:239], v[254:255]
	v_pk_mul_f32 v[148:149], v[240:241], v[148:149]
	v_cvt_pk_bf16_f32 v242, v254, v255
	v_cvt_pk_bf16_f32 v243, v148, v149
	v_mov_b32_dpp v246, v28 row_ror:1 row_mask:0xf bank_mask:0xf
	v_mov_b32_dpp v250, v28 row_ror:2 row_mask:0xf bank_mask:0xf
	v_mov_b32_dpp v247, v29 row_ror:1 row_mask:0xf bank_mask:0xf
	v_mov_b32_dpp v251, v29 row_ror:2 row_mask:0xf bank_mask:0xf
	v_mov_b32_dpp v248, v30 row_ror:1 row_mask:0xf bank_mask:0xf
	v_mov_b32_dpp v252, v30 row_ror:2 row_mask:0xf bank_mask:0xf
	v_mov_b32_dpp v249, v31 row_ror:1 row_mask:0xf bank_mask:0xf
	v_mov_b32_dpp v253, v31 row_ror:2 row_mask:0xf bank_mask:0xf
	v_mov_b32_dpp v246, v20 row_shr:1 row_mask:0xf bank_mask:0xf
	v_mov_b32_dpp v250, v20 row_shr:2 row_mask:0xf bank_mask:0xf
	v_mov_b32_dpp v247, v21 row_shr:1 row_mask:0xf bank_mask:0xf
	v_mov_b32_dpp v251, v21 row_shr:2 row_mask:0xf bank_mask:0xf
	v_mov_b32_dpp v248, v22 row_shr:1 row_mask:0xf bank_mask:0xf
	v_mov_b32_dpp v252, v22 row_shr:2 row_mask:0xf bank_mask:0xf
	v_mov_b32_dpp v249, v23 row_shr:1 row_mask:0xf bank_mask:0xf
	v_mov_b32_dpp v253, v23 row_shr:2 row_mask:0xf bank_mask:0xf
	v_pk_fma_f32 v[254:255], v[174:175], v[250:251], v[136:137]
	v_pk_fma_f32 v[148:149], v[176:177], v[252:253], v[138:139]
	v_pk_fma_f32 v[254:255], v[190:191], v[246:247], v[254:255]
	v_pk_fma_f32 v[148:149], v[192:193], v[248:249], v[148:149]
	v_pk_fma_f32 v[254:255], v[206:207], v[20:21], v[254:255]
	v_pk_fma_f32 v[148:149], v[208:209], v[22:23], v[148:149]
	v_and_b32_e32 v246, 0x7fffffff, v254
	v_and_b32_e32 v247, 0x7fffffff, v255
	v_and_b32_e32 v250, 0x7fffffff, v148
	v_and_b32_e32 v251, 0x7fffffff, v149
	v_pk_fma_f32 v[246:247], v[246:247], s[38:39], 1.0 op_sel_hi:[1,0,0]
	v_pk_fma_f32 v[250:251], v[250:251], s[38:39], 1.0 op_sel_hi:[1,0,0]
	v_pk_mul_f32 v[248:249], v[254:255], v[254:255]
	v_pk_mul_f32 v[252:253], v[148:149], v[148:149]
	v_rcp_f32_e32 v246, v246
	v_rcp_f32_e32 v247, v247
	v_rcp_f32_e32 v250, v250
	v_rcp_f32_e32 v251, v251
	v_pk_mul_f32 v[248:249], v[248:249], s[72:73] op_sel_hi:[1,0]
	v_pk_mul_f32 v[252:253], v[252:253], s[72:73] op_sel_hi:[1,0]
	v_mov_b64_e32 v[238:239], s[64:65]
	v_mov_b64_e32 v[240:241], s[64:65]
	v_exp_f32_e32 v248, v248
	v_exp_f32_e32 v249, v249
	v_exp_f32_e32 v252, v252
	v_exp_f32_e32 v253, v253
	v_pk_fma_f32 v[238:239], v[246:247], s[62:63], v[238:239] op_sel_hi:[1,0,0]
	v_pk_fma_f32 v[240:241], v[250:251], s[62:63], v[240:241] op_sel_hi:[1,0,0]
	v_pk_fma_f32 v[238:239], v[246:247], v[238:239], s[66:67] op_sel_hi:[1,1,0]
	v_pk_fma_f32 v[240:241], v[250:251], v[240:241], s[66:67] op_sel_hi:[1,1,0]
	v_pk_fma_f32 v[238:239], v[246:247], v[238:239], s[68:69] op_sel_hi:[1,1,0]
	v_pk_fma_f32 v[240:241], v[250:251], v[240:241], s[68:69] op_sel_hi:[1,1,0]
	v_pk_fma_f32 v[238:239], v[246:247], v[238:239], s[70:71] op_sel_hi:[1,1,0]
	v_pk_fma_f32 v[240:241], v[250:251], v[240:241], s[70:71] op_sel_hi:[1,1,0]
	v_pk_mul_f32 v[238:239], v[246:247], v[238:239]
	v_pk_mul_f32 v[240:241], v[250:251], v[240:241]
	v_pk_mul_f32 v[238:239], v[248:249], v[238:239]
	v_pk_mul_f32 v[240:241], v[252:253], v[240:241]
	v_cmp_gt_f32_e64 vcc, 0, v254
	v_cmp_gt_f32_e64 s[56:57], 0, v148
	v_cmp_gt_f32_e64 s[14:15], 0, v255
	v_cmp_gt_f32_e64 s[92:93], 0, v149
	v_pk_mul_f32 v[248:249], v[254:255], v[238:239]
; __device__ __forceinline__ f32x2 gelu_pk(f32x2 v) {
;     const f32x2 av = __builtin_elementwise_abs(v), d = av * 0.2316418882f + 1.0f;
;     __device__ __forceinline__ void operator()(const f32x4 (&acc)[2][2][4][2], const Unit& u, int wr, int wc, int fr, int fq) const {
;     ...
; #pragma unroll
;                     for (int m = 0; m < 4; ++m) {
;                         f32x4 cv;
;                         if (!samp) {
;                             const f32x4 prev = m ? v[m - 1] : hv;
; #pragma unroll
;                             for (int e = 0; e < 4; ++e) {
;                                 const int vi = __float_as_int(v[m][e]), pi = __float_as_int(prev[e]);
;                                 const int o1 = __builtin_amdgcn_mov_dpp(pi, 0x121, 0xf, 0xf, false);
;                                 const int o2 = __builtin_amdgcn_mov_dpp(pi, 0x122, 0xf, 0xf, false);
;                                 const float p1 = __int_as_float(__builtin_amdgcn_update_dpp(o1, vi, 0x111, 0xf, 0xf, false));
;                                 const float p2 = __int_as_float(__builtin_amdgcn_update_dpp(o2, vi, 0x112, 0xf, 0xf, false));
;                                 cv[e] = cb[e] + cw0[e] * p2 + cw1[e] * p1 + cw2[e] * v[m][e];
;                             }
;                         } else {
;                             const int ns = rowb + 16 * m + fr - MP;
;                             f32x4 s0 = (f32x4){0.f, 0.f, 0.f, 0.f}, s1 = s0;
;                             if (ns < NS) {
;                                 s0 = *(const f32x4*)(state + (size_t)(ns * 2 + 0) * FF2 + oc); s1 = *(const f32x4*)(state + (size_t)(ns * 2 + 1) * FF2 + oc);
;                                 *(f32x4*)(ncs + (size_t)(ns * 2 + 0) * FF2 + oc) = s1; *(f32x4*)(ncs + (size_t)(ns * 2 + 1) * FF2 + oc) = v[m];
;                             }
;                             cv = cb + cw0 * s0 + cw1 * s1 + cw2 * v[m];
;                         }
;                         if (bj == 0) cg[m] = gelu4(cv);
;                         else {
;                             const f32x4 r = cg[m] * cv;
;                             v2u w; w.x = cvt_pk_bf16(r[0], r[1]); w.y = cvt_pk_bf16(r[2], r[3]);
;                             *(v2u*)(ACT + (size_t)(rowb + 16 * m + fr) * FF + 128 * u.pn + 32 * wc + 8 * fq + 4 * n) = w;
;                         }
	v_pk_mul_f32 v[252:253], v[148:149], v[240:241]
	v_pk_fma_f32 v[238:239], v[254:255], v[238:239], v[254:255] neg_lo:[1,0,0] neg_hi:[1,0,0]
	v_pk_fma_f32 v[240:241], v[148:149], v[240:241], v[148:149] neg_lo:[1,0,0] neg_hi:[1,0,0]
	v_cndmask_b32_e64 v238, v238, v248, vcc
	v_cndmask_b32_e64 v240, v240, v252, s[56:57]
	v_cndmask_b32_e64 v239, v239, v249, s[14:15]
	v_cndmask_b32_e64 v241, v241, v253, s[92:93]
	v_mov_b32_dpp v246, v12 row_ror:1 row_mask:0xf bank_mask:0xf
	v_mov_b32_dpp v250, v12 row_ror:2 row_mask:0xf bank_mask:0xf
	v_mov_b32_dpp v247, v13 row_ror:1 row_mask:0xf bank_mask:0xf
	v_mov_b32_dpp v251, v13 row_ror:2 row_mask:0xf bank_mask:0xf
	v_mov_b32_dpp v248, v14 row_ror:1 row_mask:0xf bank_mask:0xf
	v_mov_b32_dpp v252, v14 row_ror:2 row_mask:0xf bank_mask:0xf
	v_mov_b32_dpp v249, v15 row_ror:1 row_mask:0xf bank_mask:0xf
	v_mov_b32_dpp v253, v15 row_ror:2 row_mask:0xf bank_mask:0xf
	v_mov_b32_dpp v246, v4 row_shr:1 row_mask:0xf bank_mask:0xf
	v_mov_b32_dpp v250, v4 row_shr:2 row_mask:0xf bank_mask:0xf
	v_mov_b32_dpp v247, v5 row_shr:1 row_mask:0xf bank_mask:0xf
	v_mov_b32_dpp v251, v5 row_shr:2 row_mask:0xf bank_mask:0xf
	v_mov_b32_dpp v248, v6 row_shr:1 row_mask:0xf bank_mask:0xf
	v_mov_b32_dpp v252, v6 row_shr:2 row_mask:0xf bank_mask:0xf
	v_mov_b32_dpp v249, v7 row_shr:1 row_mask:0xf bank_mask:0xf
	v_mov_b32_dpp v253, v7 row_shr:2 row_mask:0xf bank_mask:0xf
	v_pk_fma_f32 v[254:255], v[182:183], v[250:251], v[144:145]
	v_pk_fma_f32 v[148:149], v[184:185], v[252:253], v[146:147]
	v_pk_fma_f32 v[254:255], v[198:199], v[246:247], v[254:255]
	v_pk_fma_f32 v[148:149], v[200:201], v[248:249], v[148:149]
	v_pk_fma_f32 v[254:255], v[128:129], v[4:5], v[254:255]
	v_pk_fma_f32 v[148:149], v[130:131], v[6:7], v[148:149]
	v_pk_mul_f32 v[254:255], v[238:239], v[254:255]
	v_pk_mul_f32 v[148:149], v[240:241], v[148:149]
	v_cvt_pk_bf16_f32 v244, v254, v255
	v_cvt_pk_bf16_f32 v245, v148, v149
	s_add_u32 s56, s46, 0xc6000
	s_addc_u32 s57, s47, 0
	global_store_dwordx4 v151, v[242:245], s[56:57]
	v_mov_b32_dpp v246, v52 row_ror:1 row_mask:0xf bank_mask:0xf
	v_mov_b32_dpp v250, v52 row_ror:2 row_mask:0xf bank_mask:0xf
	v_mov_b32_dpp v247, v53 row_ror:1 row_mask:0xf bank_mask:0xf
	v_mov_b32_dpp v251, v53 row_ror:2 row_mask:0xf bank_mask:0xf
	v_mov_b32_dpp v248, v54 row_ror:1 row_mask:0xf bank_mask:0xf
	v_mov_b32_dpp v252, v54 row_ror:2 row_mask:0xf bank_mask:0xf
	v_mov_b32_dpp v249, v55 row_ror:1 row_mask:0xf bank_mask:0xf
	v_mov_b32_dpp v253, v55 row_ror:2 row_mask:0xf bank_mask:0xf
	v_mov_b32_dpp v246, v48 row_shr:1 row_mask:0xf bank_mask:0xf
	v_mov_b32_dpp v250, v48 row_shr:2 row_mask:0xf bank_mask:0xf
	v_mov_b32_dpp v247, v49 row_shr:1 row_mask:0xf bank_mask:0xf
	v_mov_b32_dpp v251, v49 row_shr:2 row_mask:0xf bank_mask:0xf
	v_mov_b32_dpp v248, v50 row_shr:1 row_mask:0xf bank_mask:0xf
	v_mov_b32_dpp v252, v50 row_shr:2 row_mask:0xf bank_mask:0xf
	v_mov_b32_dpp v249, v51 row_shr:1 row_mask:0xf bank_mask:0xf
	v_mov_b32_dpp v253, v51 row_shr:2 row_mask:0xf bank_mask:0xf
	v_pk_fma_f32 v[254:255], v[170:171], v[250:251], v[132:133]
	v_pk_fma_f32 v[148:149], v[172:173], v[252:253], v[134:135]
	v_pk_fma_f32 v[254:255], v[186:187], v[246:247], v[254:255]
	v_pk_fma_f32 v[148:149], v[188:189], v[248:249], v[148:149]
	v_pk_fma_f32 v[254:255], v[202:203], v[48:49], v[254:255]
	v_pk_fma_f32 v[148:149], v[204:205], v[50:51], v[148:149]
	v_and_b32_e32 v246, 0x7fffffff, v254
	v_and_b32_e32 v247, 0x7fffffff, v255
	v_and_b32_e32 v250, 0x7fffffff, v148
	v_and_b32_e32 v251, 0x7fffffff, v149
	v_pk_fma_f32 v[246:247], v[246:247], s[38:39], 1.0 op_sel_hi:[1,0,0]
	v_pk_fma_f32 v[250:251], v[250:251], s[38:39], 1.0 op_sel_hi:[1,0,0]
	v_pk_mul_f32 v[248:249], v[254:255], v[254:255]
	v_pk_mul_f32 v[252:253], v[148:149], v[148:149]
	v_rcp_f32_e32 v246, v246
	v_rcp_f32_e32 v247, v247
	v_rcp_f32_e32 v250, v250
	v_rcp_f32_e32 v251, v251
	v_pk_mul_f32 v[248:249], v[248:249], s[72:73] op_sel_hi:[1,0]
	v_pk_mul_f32 v[252:253], v[252:253], s[72:73] op_sel_hi:[1,0]
	v_mov_b64_e32 v[238:239], s[64:65]
	v_mov_b64_e32 v[240:241], s[64:65]
	v_exp_f32_e32 v248, v248
	v_exp_f32_e32 v249, v249
	v_exp_f32_e32 v252, v252
	v_exp_f32_e32 v253, v253
	v_pk_fma_f32 v[238:239], v[246:247], s[62:63], v[238:239] op_sel_hi:[1,0,0]
	v_pk_fma_f32 v[240:241], v[250:251], s[62:63], v[240:241] op_sel_hi:[1,0,0]
	v_pk_fma_f32 v[238:239], v[246:247], v[238:239], s[66:67] op_sel_hi:[1,1,0]
	v_pk_fma_f32 v[240:241], v[250:251], v[240:241], s[66:67] op_sel_hi:[1,1,0]
	v_pk_fma_f32 v[238:239], v[246:247], v[238:239], s[68:69] op_sel_hi:[1,1,0]
	v_pk_fma_f32 v[240:241], v[250:251], v[240:241], s[68:69] op_sel_hi:[1,1,0]
	v_pk_fma_f32 v[238:239], v[246:247], v[238:239], s[70:71] op_sel_hi:[1,1,0]
	v_pk_fma_f32 v[240:241], v[250:251], v[240:241], s[70:71] op_sel_hi:[1,1,0]
	v_pk_mul_f32 v[238:239], v[246:247], v[238:239]
	v_pk_mul_f32 v[240:241], v[250:251], v[240:241]
	v_pk_mul_f32 v[238:239], v[248:249], v[238:239]
	v_pk_mul_f32 v[240:241], v[252:253], v[240:241]
	v_cmp_gt_f32_e64 vcc, 0, v254
	v_cmp_gt_f32_e64 s[56:57], 0, v148
	v_cmp_gt_f32_e64 s[14:15], 0, v255
	v_cmp_gt_f32_e64 s[92:93], 0, v149
	v_pk_mul_f32 v[248:249], v[254:255], v[238:239]
	v_pk_mul_f32 v[252:253], v[148:149], v[240:241]
	v_pk_fma_f32 v[238:239], v[254:255], v[238:239], v[254:255] neg_lo:[1,0,0] neg_hi:[1,0,0]
	v_pk_fma_f32 v[240:241], v[148:149], v[240:241], v[148:149] neg_lo:[1,0,0] neg_hi:[1,0,0]
	v_cndmask_b32_e64 v238, v238, v248, vcc
	v_cndmask_b32_e64 v240, v240, v252, s[56:57]
	v_cndmask_b32_e64 v239, v239, v249, s[14:15]
	v_cndmask_b32_e64 v241, v241, v253, s[92:93]
	v_mov_b32_dpp v246, v36 row_ror:1 row_mask:0xf bank_mask:0xf
; __device__ __forceinline__ f32x2 gelu_pk(f32x2 v) {
;     const f32x2 av = __builtin_elementwise_abs(v), d = av * 0.2316418882f + 1.0f;
;     __device__ __forceinline__ void operator()(const f32x4 (&acc)[2][2][4][2], const Unit& u, int wr, int wc, int fr, int fq) const {
;     ...
; #pragma unroll
;                     for (int m = 0; m < 4; ++m) {
;                         f32x4 cv;
;                         if (!samp) {
;                             const f32x4 prev = m ? v[m - 1] : hv;
; #pragma unroll
;                             for (int e = 0; e < 4; ++e) {
;                                 const int vi = __float_as_int(v[m][e]), pi = __float_as_int(prev[e]);
;                                 const int o1 = __builtin_amdgcn_mov_dpp(pi, 0x121, 0xf, 0xf, false);
;                                 const int o2 = __builtin_amdgcn_mov_dpp(pi, 0x122, 0xf, 0xf, false);
;                                 const float p1 = __int_as_float(__builtin_amdgcn_update_dpp(o1, vi, 0x111, 0xf, 0xf, false));
;                                 const float p2 = __int_as_float(__builtin_amdgcn_update_dpp(o2, vi, 0x112, 0xf, 0xf, false));
;                                 cv[e] = cb[e] + cw0[e] * p2 + cw1[e] * p1 + cw2[e] * v[m][e];
;                             }
;                         } else {
;                             const int ns = rowb + 16 * m + fr - MP;
;                             f32x4 s0 = (f32x4){0.f, 0.f, 0.f, 0.f}, s1 = s0;
;                             if (ns < NS) {
;                                 s0 = *(const f32x4*)(state + (size_t)(ns * 2 + 0) * FF2 + oc); s1 = *(const f32x4*)(state + (size_t)(ns * 2 + 1) * FF2 + oc);
;                                 *(f32x4*)(ncs + (size_t)(ns * 2 + 0) * FF2 + oc) = s1; *(f32x4*)(ncs + (size_t)(ns * 2 + 1) * FF2 + oc) = v[m];
;                             }
;                             cv = cb + cw0 * s0 + cw1 * s1 + cw2 * v[m];
;                         }
;                         if (bj == 0) cg[m] = gelu4(cv);
;                         else {
;                             const f32x4 r = cg[m] * cv;
;                             v2u w; w.x = cvt_pk_bf16(r[0], r[1]); w.y = cvt_pk_bf16(r[2], r[3]);
;                             *(v2u*)(ACT + (size_t)(rowb + 16 * m + fr) * FF + 128 * u.pn + 32 * wc + 8 * fq + 4 * n) = w;
;                         }
	v_mov_b32_dpp v250, v36 row_ror:2 row_mask:0xf bank_mask:0xf
	v_mov_b32_dpp v247, v37 row_ror:1 row_mask:0xf bank_mask:0xf
	v_mov_b32_dpp v251, v37 row_ror:2 row_mask:0xf bank_mask:0xf
	v_mov_b32_dpp v248, v38 row_ror:1 row_mask:0xf bank_mask:0xf
	v_mov_b32_dpp v252, v38 row_ror:2 row_mask:0xf bank_mask:0xf
	v_mov_b32_dpp v249, v39 row_ror:1 row_mask:0xf bank_mask:0xf
	v_mov_b32_dpp v253, v39 row_ror:2 row_mask:0xf bank_mask:0xf
	v_mov_b32_dpp v246, v32 row_shr:1 row_mask:0xf bank_mask:0xf
	v_mov_b32_dpp v250, v32 row_shr:2 row_mask:0xf bank_mask:0xf
	v_mov_b32_dpp v247, v33 row_shr:1 row_mask:0xf bank_mask:0xf
	v_mov_b32_dpp v251, v33 row_shr:2 row_mask:0xf bank_mask:0xf
	v_mov_b32_dpp v248, v34 row_shr:1 row_mask:0xf bank_mask:0xf
	v_mov_b32_dpp v252, v34 row_shr:2 row_mask:0xf bank_mask:0xf
	v_mov_b32_dpp v249, v35 row_shr:1 row_mask:0xf bank_mask:0xf
	v_mov_b32_dpp v253, v35 row_shr:2 row_mask:0xf bank_mask:0xf
	v_pk_fma_f32 v[254:255], v[178:179], v[250:251], v[140:141]
	v_pk_fma_f32 v[148:149], v[180:181], v[252:253], v[142:143]
	v_pk_fma_f32 v[254:255], v[194:195], v[246:247], v[254:255]
	v_pk_fma_f32 v[148:149], v[196:197], v[248:249], v[148:149]
	v_pk_fma_f32 v[254:255], v[210:211], v[32:33], v[254:255]
	v_pk_fma_f32 v[148:149], v[212:213], v[34:35], v[148:149]
	v_pk_mul_f32 v[254:255], v[238:239], v[254:255]
	v_pk_mul_f32 v[148:149], v[240:241], v[148:149]
	v_cvt_pk_bf16_f32 v242, v254, v255
	v_cvt_pk_bf16_f32 v243, v148, v149
	v_mov_b32_dpp v246, v20 row_ror:1 row_mask:0xf bank_mask:0xf
	v_mov_b32_dpp v250, v20 row_ror:2 row_mask:0xf bank_mask:0xf
	v_mov_b32_dpp v247, v21 row_ror:1 row_mask:0xf bank_mask:0xf
	v_mov_b32_dpp v251, v21 row_ror:2 row_mask:0xf bank_mask:0xf
	v_mov_b32_dpp v248, v22 row_ror:1 row_mask:0xf bank_mask:0xf
	v_mov_b32_dpp v252, v22 row_ror:2 row_mask:0xf bank_mask:0xf
	v_mov_b32_dpp v249, v23 row_ror:1 row_mask:0xf bank_mask:0xf
	v_mov_b32_dpp v253, v23 row_ror:2 row_mask:0xf bank_mask:0xf
	v_mov_b32_dpp v246, v16 row_shr:1 row_mask:0xf bank_mask:0xf
	v_mov_b32_dpp v250, v16 row_shr:2 row_mask:0xf bank_mask:0xf
	v_mov_b32_dpp v247, v17 row_shr:1 row_mask:0xf bank_mask:0xf
	v_mov_b32_dpp v251, v17 row_shr:2 row_mask:0xf bank_mask:0xf
	v_mov_b32_dpp v248, v18 row_shr:1 row_mask:0xf bank_mask:0xf
	v_mov_b32_dpp v252, v18 row_shr:2 row_mask:0xf bank_mask:0xf
	v_mov_b32_dpp v249, v19 row_shr:1 row_mask:0xf bank_mask:0xf
	v_mov_b32_dpp v253, v19 row_shr:2 row_mask:0xf bank_mask:0xf
	v_pk_fma_f32 v[254:255], v[174:175], v[250:251], v[136:137]
	v_pk_fma_f32 v[148:149], v[176:177], v[252:253], v[138:139]
	v_pk_fma_f32 v[254:255], v[190:191], v[246:247], v[254:255]
	v_pk_fma_f32 v[148:149], v[192:193], v[248:249], v[148:149]
	v_pk_fma_f32 v[254:255], v[206:207], v[16:17], v[254:255]
	v_pk_fma_f32 v[148:149], v[208:209], v[18:19], v[148:149]
	v_and_b32_e32 v246, 0x7fffffff, v254
	v_and_b32_e32 v247, 0x7fffffff, v255
	v_and_b32_e32 v250, 0x7fffffff, v148
	v_and_b32_e32 v251, 0x7fffffff, v149
	v_pk_fma_f32 v[246:247], v[246:247], s[38:39], 1.0 op_sel_hi:[1,0,0]
	v_pk_fma_f32 v[250:251], v[250:251], s[38:39], 1.0 op_sel_hi:[1,0,0]
	v_pk_mul_f32 v[248:249], v[254:255], v[254:255]
	v_pk_mul_f32 v[252:253], v[148:149], v[148:149]
	v_rcp_f32_e32 v246, v246
	v_rcp_f32_e32 v247, v247
	v_rcp_f32_e32 v250, v250
	v_rcp_f32_e32 v251, v251
	v_pk_mul_f32 v[248:249], v[248:249], s[72:73] op_sel_hi:[1,0]
	v_pk_mul_f32 v[252:253], v[252:253], s[72:73] op_sel_hi:[1,0]
	v_mov_b64_e32 v[238:239], s[64:65]
	v_mov_b64_e32 v[240:241], s[64:65]
	v_exp_f32_e32 v248, v248
	v_exp_f32_e32 v249, v249
	v_exp_f32_e32 v252, v252
	v_exp_f32_e32 v253, v253
	v_pk_fma_f32 v[238:239], v[246:247], s[62:63], v[238:239] op_sel_hi:[1,0,0]
	v_pk_fma_f32 v[240:241], v[250:251], s[62:63], v[240:241] op_sel_hi:[1,0,0]
	v_pk_fma_f32 v[238:239], v[246:247], v[238:239], s[66:67] op_sel_hi:[1,1,0]
	v_pk_fma_f32 v[240:241], v[250:251], v[240:241], s[66:67] op_sel_hi:[1,1,0]
	v_pk_fma_f32 v[238:239], v[246:247], v[238:239], s[68:69] op_sel_hi:[1,1,0]
	v_pk_fma_f32 v[240:241], v[250:251], v[240:241], s[68:69] op_sel_hi:[1,1,0]
	v_pk_fma_f32 v[238:239], v[246:247], v[238:239], s[70:71] op_sel_hi:[1,1,0]
	v_pk_fma_f32 v[240:241], v[250:251], v[240:241], s[70:71] op_sel_hi:[1,1,0]
	v_pk_mul_f32 v[238:239], v[246:247], v[238:239]
	v_pk_mul_f32 v[240:241], v[250:251], v[240:241]
	v_pk_mul_f32 v[238:239], v[248:249], v[238:239]
	v_pk_mul_f32 v[240:241], v[252:253], v[240:241]
	v_cmp_gt_f32_e64 vcc, 0, v254
	v_cmp_gt_f32_e64 s[56:57], 0, v148
	v_cmp_gt_f32_e64 s[14:15], 0, v255
	v_cmp_gt_f32_e64 s[92:93], 0, v149
	v_pk_mul_f32 v[248:249], v[254:255], v[238:239]
	v_pk_mul_f32 v[252:253], v[148:149], v[240:241]
	v_pk_fma_f32 v[238:239], v[254:255], v[238:239], v[254:255] neg_lo:[1,0,0] neg_hi:[1,0,0]
	v_pk_fma_f32 v[240:241], v[148:149], v[240:241], v[148:149] neg_lo:[1,0,0] neg_hi:[1,0,0]
	v_cndmask_b32_e64 v238, v238, v248, vcc
	v_cndmask_b32_e64 v240, v240, v252, s[56:57]
	v_cndmask_b32_e64 v239, v239, v249, s[14:15]
	v_cndmask_b32_e64 v241, v241, v253, s[92:93]
	v_mov_b32_dpp v246, v4 row_ror:1 row_mask:0xf bank_mask:0xf
	v_mov_b32_dpp v250, v4 row_ror:2 row_mask:0xf bank_mask:0xf
	v_mov_b32_dpp v247, v5 row_ror:1 row_mask:0xf bank_mask:0xf
	v_mov_b32_dpp v251, v5 row_ror:2 row_mask:0xf bank_mask:0xf
	v_mov_b32_dpp v248, v6 row_ror:1 row_mask:0xf bank_mask:0xf
	v_mov_b32_dpp v252, v6 row_ror:2 row_mask:0xf bank_mask:0xf
	v_mov_b32_dpp v249, v7 row_ror:1 row_mask:0xf bank_mask:0xf
	v_mov_b32_dpp v253, v7 row_ror:2 row_mask:0xf bank_mask:0xf
	v_mov_b32_dpp v246, v0 row_shr:1 row_mask:0xf bank_mask:0xf
	v_mov_b32_dpp v250, v0 row_shr:2 row_mask:0xf bank_mask:0xf
; __device__ __forceinline__ f32x2 gelu_pk(f32x2 v) {
;     const f32x2 av = __builtin_elementwise_abs(v), d = av * 0.2316418882f + 1.0f;
;     __device__ __forceinline__ void operator()(const f32x4 (&acc)[2][2][4][2], const Unit& u, int wr, int wc, int fr, int fq) const {
;     ...
; #pragma unroll
;                     for (int m = 0; m < 4; ++m) {
;                         f32x4 cv;
;                         if (!samp) {
;                             const f32x4 prev = m ? v[m - 1] : hv;
; #pragma unroll
;                             for (int e = 0; e < 4; ++e) {
;                                 const int vi = __float_as_int(v[m][e]), pi = __float_as_int(prev[e]);
;                                 const int o1 = __builtin_amdgcn_mov_dpp(pi, 0x121, 0xf, 0xf, false);
;                                 const int o2 = __builtin_amdgcn_mov_dpp(pi, 0x122, 0xf, 0xf, false);
;                                 const float p1 = __int_as_float(__builtin_amdgcn_update_dpp(o1, vi, 0x111, 0xf, 0xf, false));
;                                 const float p2 = __int_as_float(__builtin_amdgcn_update_dpp(o2, vi, 0x112, 0xf, 0xf, false));
;                                 cv[e] = cb[e] + cw0[e] * p2 + cw1[e] * p1 + cw2[e] * v[m][e];
;                             }
;                         } else {
;                             const int ns = rowb + 16 * m + fr - MP;
;                             f32x4 s0 = (f32x4){0.f, 0.f, 0.f, 0.f}, s1 = s0;
;                             if (ns < NS) {
;                                 s0 = *(const f32x4*)(state + (size_t)(ns * 2 + 0) * FF2 + oc); s1 = *(const f32x4*)(state + (size_t)(ns * 2 + 1) * FF2 + oc);
;                                 *(f32x4*)(ncs + (size_t)(ns * 2 + 0) * FF2 + oc) = s1; *(f32x4*)(ncs + (size_t)(ns * 2 + 1) * FF2 + oc) = v[m];
;                             }
;                             cv = cb + cw0 * s0 + cw1 * s1 + cw2 * v[m];
;                         }
;                         if (bj == 0) cg[m] = gelu4(cv);
;                         else {
;                             const f32x4 r = cg[m] * cv;
;                             v2u w; w.x = cvt_pk_bf16(r[0], r[1]); w.y = cvt_pk_bf16(r[2], r[3]);
;                             *(v2u*)(ACT + (size_t)(rowb + 16 * m + fr) * FF + 128 * u.pn + 32 * wc + 8 * fq + 4 * n) = w;
;                         }
	v_mov_b32_dpp v247, v1 row_shr:1 row_mask:0xf bank_mask:0xf
	v_mov_b32_dpp v251, v1 row_shr:2 row_mask:0xf bank_mask:0xf
	v_mov_b32_dpp v248, v2 row_shr:1 row_mask:0xf bank_mask:0xf
	v_mov_b32_dpp v252, v2 row_shr:2 row_mask:0xf bank_mask:0xf
	v_mov_b32_dpp v249, v3 row_shr:1 row_mask:0xf bank_mask:0xf
	v_mov_b32_dpp v253, v3 row_shr:2 row_mask:0xf bank_mask:0xf
	v_pk_fma_f32 v[254:255], v[182:183], v[250:251], v[144:145]
	v_pk_fma_f32 v[148:149], v[184:185], v[252:253], v[146:147]
	v_pk_fma_f32 v[254:255], v[198:199], v[246:247], v[254:255]
	v_pk_fma_f32 v[148:149], v[200:201], v[248:249], v[148:149]
	v_pk_fma_f32 v[254:255], v[128:129], v[0:1], v[254:255]
	v_pk_fma_f32 v[148:149], v[130:131], v[2:3], v[148:149]
	v_pk_mul_f32 v[254:255], v[238:239], v[254:255]
	v_pk_mul_f32 v[148:149], v[240:241], v[148:149]
	v_cvt_pk_bf16_f32 v244, v254, v255
	v_cvt_pk_bf16_f32 v245, v148, v149
	s_add_u32 s56, s46, 0xdc000
	s_addc_u32 s57, s47, 0
	global_store_dwordx4 v151, v[242:245], s[56:57]
	v_mov_b32_dpp v246, v48 row_ror:1 row_mask:0xf bank_mask:0xf
	v_mov_b32_dpp v250, v48 row_ror:2 row_mask:0xf bank_mask:0xf
	v_mov_b32_dpp v247, v49 row_ror:1 row_mask:0xf bank_mask:0xf
	v_mov_b32_dpp v251, v49 row_ror:2 row_mask:0xf bank_mask:0xf
	v_mov_b32_dpp v248, v50 row_ror:1 row_mask:0xf bank_mask:0xf
	v_mov_b32_dpp v252, v50 row_ror:2 row_mask:0xf bank_mask:0xf
	v_mov_b32_dpp v249, v51 row_ror:1 row_mask:0xf bank_mask:0xf
	v_mov_b32_dpp v253, v51 row_ror:2 row_mask:0xf bank_mask:0xf
	v_mov_b32_dpp v246, v56 row_shr:1 row_mask:0xf bank_mask:0xf
	v_mov_b32_dpp v250, v56 row_shr:2 row_mask:0xf bank_mask:0xf
	v_mov_b32_dpp v247, v57 row_shr:1 row_mask:0xf bank_mask:0xf
	v_mov_b32_dpp v251, v57 row_shr:2 row_mask:0xf bank_mask:0xf
	v_mov_b32_dpp v248, v58 row_shr:1 row_mask:0xf bank_mask:0xf
	v_mov_b32_dpp v252, v58 row_shr:2 row_mask:0xf bank_mask:0xf
	v_mov_b32_dpp v249, v59 row_shr:1 row_mask:0xf bank_mask:0xf
	v_mov_b32_dpp v253, v59 row_shr:2 row_mask:0xf bank_mask:0xf
	v_pk_fma_f32 v[254:255], v[170:171], v[250:251], v[132:133]
	v_pk_fma_f32 v[148:149], v[172:173], v[252:253], v[134:135]
	v_pk_fma_f32 v[254:255], v[186:187], v[246:247], v[254:255]
	v_pk_fma_f32 v[148:149], v[188:189], v[248:249], v[148:149]
	v_pk_fma_f32 v[254:255], v[202:203], v[56:57], v[254:255]
	v_pk_fma_f32 v[148:149], v[204:205], v[58:59], v[148:149]
	v_and_b32_e32 v246, 0x7fffffff, v254
	v_and_b32_e32 v247, 0x7fffffff, v255
	v_and_b32_e32 v250, 0x7fffffff, v148
	v_and_b32_e32 v251, 0x7fffffff, v149
	v_pk_fma_f32 v[246:247], v[246:247], s[38:39], 1.0 op_sel_hi:[1,0,0]
	v_pk_fma_f32 v[250:251], v[250:251], s[38:39], 1.0 op_sel_hi:[1,0,0]
	v_pk_mul_f32 v[248:249], v[254:255], v[254:255]
	v_pk_mul_f32 v[252:253], v[148:149], v[148:149]
	v_rcp_f32_e32 v246, v246
	v_rcp_f32_e32 v247, v247
	v_rcp_f32_e32 v250, v250
	v_rcp_f32_e32 v251, v251
	v_pk_mul_f32 v[248:249], v[248:249], s[72:73] op_sel_hi:[1,0]
	v_pk_mul_f32 v[252:253], v[252:253], s[72:73] op_sel_hi:[1,0]
	v_mov_b64_e32 v[238:239], s[64:65]
	v_mov_b64_e32 v[240:241], s[64:65]
	v_exp_f32_e32 v248, v248
	v_exp_f32_e32 v249, v249
	v_exp_f32_e32 v252, v252
	v_exp_f32_e32 v253, v253
	v_pk_fma_f32 v[238:239], v[246:247], s[62:63], v[238:239] op_sel_hi:[1,0,0]
	v_pk_fma_f32 v[240:241], v[250:251], s[62:63], v[240:241] op_sel_hi:[1,0,0]
	v_pk_fma_f32 v[238:239], v[246:247], v[238:239], s[66:67] op_sel_hi:[1,1,0]
	v_pk_fma_f32 v[240:241], v[250:251], v[240:241], s[66:67] op_sel_hi:[1,1,0]
	v_pk_fma_f32 v[238:239], v[246:247], v[238:239], s[68:69] op_sel_hi:[1,1,0]
	v_pk_fma_f32 v[240:241], v[250:251], v[240:241], s[68:69] op_sel_hi:[1,1,0]
	v_pk_fma_f32 v[238:239], v[246:247], v[238:239], s[70:71] op_sel_hi:[1,1,0]
	v_pk_fma_f32 v[240:241], v[250:251], v[240:241], s[70:71] op_sel_hi:[1,1,0]
	v_pk_mul_f32 v[238:239], v[246:247], v[238:239]
	v_pk_mul_f32 v[240:241], v[250:251], v[240:241]
	v_pk_mul_f32 v[238:239], v[248:249], v[238:239]
	v_pk_mul_f32 v[240:241], v[252:253], v[240:241]
	v_cmp_gt_f32_e64 vcc, 0, v254
	v_cmp_gt_f32_e64 s[56:57], 0, v148
	v_cmp_gt_f32_e64 s[14:15], 0, v255
	v_cmp_gt_f32_e64 s[92:93], 0, v149
	v_pk_mul_f32 v[248:249], v[254:255], v[238:239]
	v_pk_mul_f32 v[252:253], v[148:149], v[240:241]
	v_pk_fma_f32 v[238:239], v[254:255], v[238:239], v[254:255] neg_lo:[1,0,0] neg_hi:[1,0,0]
	v_pk_fma_f32 v[240:241], v[148:149], v[240:241], v[148:149] neg_lo:[1,0,0] neg_hi:[1,0,0]
	v_cndmask_b32_e64 v238, v238, v248, vcc
	v_cndmask_b32_e64 v240, v240, v252, s[56:57]
	v_cndmask_b32_e64 v239, v239, v249, s[14:15]
	v_cndmask_b32_e64 v241, v241, v253, s[92:93]
	v_mov_b32_dpp v246, v32 row_ror:1 row_mask:0xf bank_mask:0xf
	v_mov_b32_dpp v250, v32 row_ror:2 row_mask:0xf bank_mask:0xf
	v_mov_b32_dpp v247, v33 row_ror:1 row_mask:0xf bank_mask:0xf
	v_mov_b32_dpp v251, v33 row_ror:2 row_mask:0xf bank_mask:0xf
	v_mov_b32_dpp v248, v34 row_ror:1 row_mask:0xf bank_mask:0xf
	v_mov_b32_dpp v252, v34 row_ror:2 row_mask:0xf bank_mask:0xf
	v_mov_b32_dpp v249, v35 row_ror:1 row_mask:0xf bank_mask:0xf
	v_mov_b32_dpp v253, v35 row_ror:2 row_mask:0xf bank_mask:0xf
	v_mov_b32_dpp v246, v40 row_shr:1 row_mask:0xf bank_mask:0xf
	v_mov_b32_dpp v250, v40 row_shr:2 row_mask:0xf bank_mask:0xf
	v_mov_b32_dpp v247, v41 row_shr:1 row_mask:0xf bank_mask:0xf
	v_mov_b32_dpp v251, v41 row_shr:2 row_mask:0xf bank_mask:0xf
	v_mov_b32_dpp v248, v42 row_shr:1 row_mask:0xf bank_mask:0xf
	v_mov_b32_dpp v252, v42 row_shr:2 row_mask:0xf bank_mask:0xf
	v_mov_b32_dpp v249, v43 row_shr:1 row_mask:0xf bank_mask:0xf
	v_mov_b32_dpp v253, v43 row_shr:2 row_mask:0xf bank_mask:0xf
	v_pk_fma_f32 v[254:255], v[178:179], v[250:251], v[140:141]
	v_pk_fma_f32 v[148:149], v[180:181], v[252:253], v[142:143]
;     __device__ __forceinline__ void operator()(const f32x4 (&acc)[2][2][4][2], const Unit& u, int wr, int wc, int fr, int fq) const {
;     ...
;                         if ((u.pm & 7) == 7 && ai == 1 && wr == 1 && fr >= 14) *(f32x4*)(ncp + (size_t)((u.pm >> 3) * 2 + (fr - 14)) * FF2 + oc) = v[3];
;                     }
; #pragma unroll
;                     for (int m = 0; m < 4; ++m) {
;                         f32x4 cv;
;                         if (!samp) {
;                             const f32x4 prev = m ? v[m - 1] : hv;
; #pragma unroll
;                             for (int e = 0; e < 4; ++e) {
;                                 const int vi = __float_as_int(v[m][e]), pi = __float_as_int(prev[e]);
;                                 const int o1 = __builtin_amdgcn_mov_dpp(pi, 0x121, 0xf, 0xf, false);
;                                 const int o2 = __builtin_amdgcn_mov_dpp(pi, 0x122, 0xf, 0xf, false);
;                                 const float p1 = __int_as_float(__builtin_amdgcn_update_dpp(o1, vi, 0x111, 0xf, 0xf, false));
;                                 const float p2 = __int_as_float(__builtin_amdgcn_update_dpp(o2, vi, 0x112, 0xf, 0xf, false));
;                                 cv[e] = cb[e] + cw0[e] * p2 + cw1[e] * p1 + cw2[e] * v[m][e];
;                             }
;                         } else {
;                             const int ns = rowb + 16 * m + fr - MP;
;                             f32x4 s0 = (f32x4){0.f, 0.f, 0.f, 0.f}, s1 = s0;
;                             if (ns < NS) {
;                                 s0 = *(const f32x4*)(state + (size_t)(ns * 2 + 0) * FF2 + oc); s1 = *(const f32x4*)(state + (size_t)(ns * 2 + 1) * FF2 + oc);
;                                 *(f32x4*)(ncs + (size_t)(ns * 2 + 0) * FF2 + oc) = s1; *(f32x4*)(ncs + (size_t)(ns * 2 + 1) * FF2 + oc) = v[m];
;                             }
;                             cv = cb + cw0 * s0 + cw1 * s1 + cw2 * v[m];
;                         }
;                         if (bj == 0) cg[m] = gelu4(cv);
;                         else {
;                             const f32x4 r = cg[m] * cv;
;                             v2u w; w.x = cvt_pk_bf16(r[0], r[1]); w.y = cvt_pk_bf16(r[2], r[3]);
;                             *(v2u*)(ACT + (size_t)(rowb + 16 * m + fr) * FF + 128 * u.pn + 32 * wc + 8 * fq + 4 * n) = w;
;                         }
	v_pk_fma_f32 v[254:255], v[194:195], v[246:247], v[254:255]
	v_pk_fma_f32 v[148:149], v[196:197], v[248:249], v[148:149]
	v_pk_fma_f32 v[254:255], v[210:211], v[40:41], v[254:255]
	v_pk_fma_f32 v[148:149], v[212:213], v[42:43], v[148:149]
	v_pk_mul_f32 v[254:255], v[238:239], v[254:255]
	v_pk_mul_f32 v[148:149], v[240:241], v[148:149]
	v_cvt_pk_bf16_f32 v242, v254, v255
	v_cvt_pk_bf16_f32 v243, v148, v149
	v_mov_b32_dpp v246, v16 row_ror:1 row_mask:0xf bank_mask:0xf
	v_mov_b32_dpp v250, v16 row_ror:2 row_mask:0xf bank_mask:0xf
	v_mov_b32_dpp v247, v17 row_ror:1 row_mask:0xf bank_mask:0xf
	v_mov_b32_dpp v251, v17 row_ror:2 row_mask:0xf bank_mask:0xf
	v_mov_b32_dpp v248, v18 row_ror:1 row_mask:0xf bank_mask:0xf
	v_mov_b32_dpp v252, v18 row_ror:2 row_mask:0xf bank_mask:0xf
	v_mov_b32_dpp v249, v19 row_ror:1 row_mask:0xf bank_mask:0xf
	v_mov_b32_dpp v253, v19 row_ror:2 row_mask:0xf bank_mask:0xf
	v_mov_b32_dpp v246, v24 row_shr:1 row_mask:0xf bank_mask:0xf
	v_mov_b32_dpp v250, v24 row_shr:2 row_mask:0xf bank_mask:0xf
	v_mov_b32_dpp v247, v25 row_shr:1 row_mask:0xf bank_mask:0xf
	v_mov_b32_dpp v251, v25 row_shr:2 row_mask:0xf bank_mask:0xf
	v_mov_b32_dpp v248, v26 row_shr:1 row_mask:0xf bank_mask:0xf
	v_mov_b32_dpp v252, v26 row_shr:2 row_mask:0xf bank_mask:0xf
	v_mov_b32_dpp v249, v27 row_shr:1 row_mask:0xf bank_mask:0xf
	v_mov_b32_dpp v253, v27 row_shr:2 row_mask:0xf bank_mask:0xf
	v_pk_fma_f32 v[254:255], v[174:175], v[250:251], v[136:137]
	v_pk_fma_f32 v[148:149], v[176:177], v[252:253], v[138:139]
	v_pk_fma_f32 v[254:255], v[190:191], v[246:247], v[254:255]
	v_pk_fma_f32 v[148:149], v[192:193], v[248:249], v[148:149]
	v_pk_fma_f32 v[254:255], v[206:207], v[24:25], v[254:255]
	v_pk_fma_f32 v[148:149], v[208:209], v[26:27], v[148:149]
	v_and_b32_e32 v246, 0x7fffffff, v254
	v_and_b32_e32 v247, 0x7fffffff, v255
	v_and_b32_e32 v250, 0x7fffffff, v148
	v_and_b32_e32 v251, 0x7fffffff, v149
	v_pk_fma_f32 v[246:247], v[246:247], s[38:39], 1.0 op_sel_hi:[1,0,0]
	v_pk_fma_f32 v[250:251], v[250:251], s[38:39], 1.0 op_sel_hi:[1,0,0]
	v_pk_mul_f32 v[248:249], v[254:255], v[254:255]
	v_pk_mul_f32 v[252:253], v[148:149], v[148:149]
	v_rcp_f32_e32 v246, v246
	v_rcp_f32_e32 v247, v247
	v_rcp_f32_e32 v250, v250
	v_rcp_f32_e32 v251, v251
	v_pk_mul_f32 v[248:249], v[248:249], s[72:73] op_sel_hi:[1,0]
	v_pk_mul_f32 v[252:253], v[252:253], s[72:73] op_sel_hi:[1,0]
	v_mov_b64_e32 v[238:239], s[64:65]
	v_mov_b64_e32 v[240:241], s[64:65]
	v_exp_f32_e32 v248, v248
	v_exp_f32_e32 v249, v249
	v_exp_f32_e32 v252, v252
	v_exp_f32_e32 v253, v253
	v_pk_fma_f32 v[238:239], v[246:247], s[62:63], v[238:239] op_sel_hi:[1,0,0]
	v_pk_fma_f32 v[240:241], v[250:251], s[62:63], v[240:241] op_sel_hi:[1,0,0]
	v_pk_fma_f32 v[238:239], v[246:247], v[238:239], s[66:67] op_sel_hi:[1,1,0]
	v_pk_fma_f32 v[240:241], v[250:251], v[240:241], s[66:67] op_sel_hi:[1,1,0]
	v_pk_fma_f32 v[238:239], v[246:247], v[238:239], s[68:69] op_sel_hi:[1,1,0]
	v_pk_fma_f32 v[240:241], v[250:251], v[240:241], s[68:69] op_sel_hi:[1,1,0]
	v_pk_fma_f32 v[238:239], v[246:247], v[238:239], s[70:71] op_sel_hi:[1,1,0]
	v_pk_fma_f32 v[240:241], v[250:251], v[240:241], s[70:71] op_sel_hi:[1,1,0]
	v_pk_mul_f32 v[238:239], v[246:247], v[238:239]
	v_pk_mul_f32 v[240:241], v[250:251], v[240:241]
	v_pk_mul_f32 v[238:239], v[248:249], v[238:239]
	v_pk_mul_f32 v[240:241], v[252:253], v[240:241]
	v_cmp_gt_f32_e64 vcc, 0, v254
	v_cmp_gt_f32_e64 s[56:57], 0, v148
	v_cmp_gt_f32_e64 s[14:15], 0, v255
	v_cmp_gt_f32_e64 s[92:93], 0, v149
	v_pk_mul_f32 v[248:249], v[254:255], v[238:239]
	v_pk_mul_f32 v[252:253], v[148:149], v[240:241]
	v_pk_fma_f32 v[238:239], v[254:255], v[238:239], v[254:255] neg_lo:[1,0,0] neg_hi:[1,0,0]
	v_pk_fma_f32 v[240:241], v[148:149], v[240:241], v[148:149] neg_lo:[1,0,0] neg_hi:[1,0,0]
	v_cndmask_b32_e64 v238, v238, v248, vcc
	v_cndmask_b32_e64 v240, v240, v252, s[56:57]
	v_cndmask_b32_e64 v239, v239, v249, s[14:15]
	v_cndmask_b32_e64 v241, v241, v253, s[92:93]
	v_mov_b32_dpp v246, v0 row_ror:1 row_mask:0xf bank_mask:0xf
	v_mov_b32_dpp v250, v0 row_ror:2 row_mask:0xf bank_mask:0xf
	v_mov_b32_dpp v247, v1 row_ror:1 row_mask:0xf bank_mask:0xf
	v_mov_b32_dpp v251, v1 row_ror:2 row_mask:0xf bank_mask:0xf
	v_mov_b32_dpp v248, v2 row_ror:1 row_mask:0xf bank_mask:0xf
	v_mov_b32_dpp v252, v2 row_ror:2 row_mask:0xf bank_mask:0xf
	v_mov_b32_dpp v249, v3 row_ror:1 row_mask:0xf bank_mask:0xf
	v_mov_b32_dpp v253, v3 row_ror:2 row_mask:0xf bank_mask:0xf
	v_mov_b32_dpp v246, v8 row_shr:1 row_mask:0xf bank_mask:0xf
	v_mov_b32_dpp v250, v8 row_shr:2 row_mask:0xf bank_mask:0xf
	v_mov_b32_dpp v247, v9 row_shr:1 row_mask:0xf bank_mask:0xf
	v_mov_b32_dpp v251, v9 row_shr:2 row_mask:0xf bank_mask:0xf
	v_mov_b32_dpp v248, v10 row_shr:1 row_mask:0xf bank_mask:0xf
	v_mov_b32_dpp v252, v10 row_shr:2 row_mask:0xf bank_mask:0xf
	v_mov_b32_dpp v249, v11 row_shr:1 row_mask:0xf bank_mask:0xf
	v_mov_b32_dpp v253, v11 row_shr:2 row_mask:0xf bank_mask:0xf
	v_pk_fma_f32 v[254:255], v[182:183], v[250:251], v[144:145]
	v_pk_fma_f32 v[148:149], v[184:185], v[252:253], v[146:147]
	v_pk_fma_f32 v[254:255], v[198:199], v[246:247], v[254:255]
	v_pk_fma_f32 v[148:149], v[200:201], v[248:249], v[148:149]
	v_pk_fma_f32 v[254:255], v[128:129], v[8:9], v[254:255]
	v_pk_fma_f32 v[148:149], v[130:131], v[10:11], v[148:149]
	v_pk_mul_f32 v[254:255], v[238:239], v[254:255]
	v_pk_mul_f32 v[148:149], v[240:241], v[148:149]
	v_cvt_pk_bf16_f32 v244, v254, v255
	v_cvt_pk_bf16_f32 v245, v148, v149
	s_add_u32 s56, s46, 0xf2000
	s_addc_u32 s57, s47, 0
	global_store_dwordx4 v151, v[242:245], s[56:57]
	s_and_b32 s14, s88, 7
	s_cmp_eq_u32 s14, 7
	s_cselect_b32 s14, s73, 0
	s_cmp_eq_u32 s14, 1
	s_cbranch_scc0 .Lfe_done
	s_lshr_b32 s14, s88, 3
	s_mul_i32 s14, s14, 0xb000
	v_mul_i32_i24_e32 v246, 0x5800, v216
	v_add_u32_e32 v246, s14, v246
	v_add_u32_e32 v246, v246, v237
	v_add_u32_e32 v247, 0x2c00, v246
	s_mov_b64 s[14:15], exec
	s_mov_b64 exec, s[10:11]
	global_store_dwordx4 v246, v[56:59], s[50:51]
	global_store_dwordx4 v246, v[24:27], s[50:51] offset:16
	global_store_dwordx4 v247, v[40:43], s[50:51]
	global_store_dwordx4 v247, v[8:11], s[50:51] offset:16
	s_mov_b64 exec, s[14:15]
.Lfe_done:
	v_readlane_b32 s90, v236, 23
	v_readlane_b32 s91, v236, 24
	s_nop 3
	s_branch .LBB0_1114

; __global__ void __launch_bounds__(512, 2) fwd_kernel(Args a) {
	.amdhsa_kernel _Z10fwd_kernel4Args
		.amdhsa_group_segment_fixed_size 0
		.amdhsa_private_segment_fixed_size 0
		.amdhsa_kernarg_size 480
		.amdhsa_user_sgpr_count 2
		.amdhsa_user_sgpr_dispatch_ptr 0
		.amdhsa_user_sgpr_queue_ptr 0
		.amdhsa_user_sgpr_kernarg_segment_ptr 1
		.amdhsa_user_sgpr_dispatch_id 0
		.amdhsa_user_sgpr_kernarg_preload_length 0
		.amdhsa_user_sgpr_kernarg_preload_offset 0
		.amdhsa_user_sgpr_private_segment_size 0
		.amdhsa_uses_dynamic_stack 0
		.amdhsa_enable_private_segment 0
		.amdhsa_system_sgpr_workgroup_id_x 1
		.amdhsa_system_sgpr_workgroup_id_y 0
		.amdhsa_system_sgpr_workgroup_id_z 0
		.amdhsa_system_sgpr_workgroup_info 0
		.amdhsa_system_vgpr_workitem_id 2
		.amdhsa_next_free_vgpr 256
		.amdhsa_next_free_sgpr 98
		.amdhsa_accum_offset 256
		.amdhsa_reserve_vcc 1
		.amdhsa_float_round_mode_32 0
		.amdhsa_float_round_mode_16_64 0
		.amdhsa_float_denorm_mode_32 3
		.amdhsa_float_denorm_mode_16_64 3
		.amdhsa_dx10_clamp 1
		.amdhsa_ieee_mode 1
		.amdhsa_fp16_overflow 0
		.amdhsa_tg_split 0
		.amdhsa_exception_fp_ieee_invalid_op 0
		.amdhsa_exception_fp_denorm_src 0
		.amdhsa_exception_fp_ieee_div_zero 0
		.amdhsa_exception_fp_ieee_overflow 0
		.amdhsa_exception_fp_ieee_underflow 0
		.amdhsa_exception_fp_ieee_inexact 0
		.amdhsa_exception_int_div_zero 0
	.end_amdhsa_kernel

; __global__ void __launch_bounds__(512, 2) fwd_kernel(Args a) {
amdhsa.kernels:
  - .agpr_count:     0
    .args:
      - .offset:         0
        .size:           224
        .value_kind:     by_value
      - .offset:         224
        .size:           4
        .value_kind:     hidden_block_count_x
      - .offset:         228
        .size:           4
        .value_kind:     hidden_block_count_y
      - .offset:         232
        .size:           4
        .value_kind:     hidden_block_count_z
      - .offset:         236
        .size:           2
        .value_kind:     hidden_group_size_x
      - .offset:         238
        .size:           2
        .value_kind:     hidden_group_size_y
      - .offset:         240
        .size:           2
        .value_kind:     hidden_group_size_z
      - .offset:         242
        .size:           2
        .value_kind:     hidden_remainder_x
      - .offset:         244
        .size:           2
        .value_kind:     hidden_remainder_y
      - .offset:         246
        .size:           2
        .value_kind:     hidden_remainder_z
      - .offset:         264
        .size:           8
        .value_kind:     hidden_global_offset_x
      - .offset:         272
        .size:           8
        .value_kind:     hidden_global_offset_y
      - .offset:         280
        .size:           8
        .value_kind:     hidden_global_offset_z
      - .offset:         288
        .size:           2
        .value_kind:     hidden_grid_dims
      - .offset:         312
        .size:           8
        .value_kind:     hidden_multigrid_sync_arg
      - .offset:         344
        .size:           4
        .value_kind:     hidden_dynamic_lds_size
    .group_segment_fixed_size: 0
    .kernarg_segment_align: 8
    .kernarg_segment_size: 480
    .language:       OpenCL C
    .language_version:
      - 2
      - 0
    .max_flat_workgroup_size: 512
    .name:           _Z10fwd_kernel4Args
    .private_segment_fixed_size: 0
    .sgpr_count:     104
    .sgpr_spill_count: 25
    .symbol:         _Z10fwd_kernel4Args.kd
    .uniform_work_group_size: 1
    .uses_dynamic_stack: false
    .vgpr_count:     256
    .vgpr_spill_count: 0
    .wavefront_size: 64
